# noS6 plus K-loop LDS-DMA issue rebalance: As[0][0] stage moved from SP2(t) to SP1(t+1), vmcnt 8->6
# speedup vs baseline: 1.0001x; 1.0001x over previous
.LBB0_116:
	ds_read_b128 v[128:131], v229
	ds_read_b128 v[132:135], v229 offset:1024
	ds_read_b128 v[136:139], v229 offset:2048
	ds_read_b128 v[140:143], v229 offset:3072
	ds_read_b128 v[144:147], v230
	ds_read_b128 v[148:151], v230 offset:1024
	ds_read_b128 v[152:155], v230 offset:2048
	ds_read_b128 v[156:159], v230 offset:3072
	s_add_u32 vcc_lo, s94, 0x100
	s_addc_u32 vcc_hi, s95, 0
	s_cmp_eq_u32 s37, 60
	s_cselect_b32 s53, s89, vcc_hi
	s_cselect_b32 s52, s93, vcc_lo
	s_cselect_b32 s97, s85, s36
	s_cselect_b32 s96, s34, s35
	v_lshl_add_u64 v[210:211], s[94:95], 0, v[178:179]
	s_add_i32 m0, s67, 0xc000
	ds_read_b128 v[160:163], v231
	ds_read_b128 v[164:167], v231 offset:1024
	ds_read_b128 v[186:189], v231 offset:2048
	ds_read_b128 v[190:193], v231 offset:3072
	ds_read_b128 v[194:197], v231 offset:4096
	ds_read_b128 v[198:201], v231 offset:5120
	ds_read_b128 v[202:205], v231 offset:6144
	ds_read_b128 v[206:209], v231 offset:7168
	global_load_lds_dwordx4 v[210:211], off
	v_lshl_add_u64 v[210:211], s[94:95], 0, v[180:181]
	s_add_i32 m0, s67, 0xe000
	s_nop 0
	global_load_lds_dwordx4 v[210:211], off
	s_waitcnt vmcnt(8)
	s_waitcnt lgkmcnt(0)
	s_barrier
	s_setprio 1
	s_waitcnt lgkmcnt(0)
	v_mfma_f32_16x16x32_bf16 v[124:127], v[128:131], v[160:163], v[124:127]
	v_mfma_f32_16x16x32_bf16 v[120:123], v[136:139], v[160:163], v[120:123]
	v_mfma_f32_16x16x32_bf16 v[112:115], v[128:131], v[186:189], v[112:115]
	v_mfma_f32_16x16x32_bf16 v[104:107], v[136:139], v[186:189], v[104:107]
	v_mfma_f32_16x16x32_bf16 v[96:99], v[128:131], v[194:197], v[96:99]
	v_mfma_f32_16x16x32_bf16 v[88:91], v[136:139], v[194:197], v[88:91]
	v_mfma_f32_16x16x32_bf16 v[80:83], v[128:131], v[202:205], v[80:83]
	v_mfma_f32_16x16x32_bf16 v[72:75], v[136:139], v[202:205], v[72:75]
	v_mfma_f32_16x16x32_bf16 v[124:127], v[132:135], v[164:167], v[124:127]
	v_mfma_f32_16x16x32_bf16 v[120:123], v[140:143], v[164:167], v[120:123]
	v_mfma_f32_16x16x32_bf16 v[112:115], v[132:135], v[190:193], v[112:115]
	v_mfma_f32_16x16x32_bf16 v[104:107], v[140:143], v[190:193], v[104:107]
	v_mfma_f32_16x16x32_bf16 v[96:99], v[132:135], v[198:201], v[96:99]
	v_mfma_f32_16x16x32_bf16 v[88:91], v[140:143], v[198:201], v[88:91]
	v_mfma_f32_16x16x32_bf16 v[80:83], v[132:135], v[206:209], v[80:83]
	v_mfma_f32_16x16x32_bf16 v[72:75], v[140:143], v[206:209], v[72:75]
	s_setprio 0
	s_setprio 1
	v_mfma_f32_16x16x32_bf16 v[116:119], v[144:147], v[160:163], v[116:119]
	v_mfma_f32_16x16x32_bf16 v[108:111], v[152:155], v[160:163], v[108:111]
	v_mfma_f32_16x16x32_bf16 v[100:103], v[144:147], v[186:189], v[100:103]
	v_mfma_f32_16x16x32_bf16 v[92:95], v[152:155], v[186:189], v[92:95]
	v_mfma_f32_16x16x32_bf16 v[84:87], v[144:147], v[194:197], v[84:87]
	v_mfma_f32_16x16x32_bf16 v[76:79], v[152:155], v[194:197], v[76:79]
	v_mfma_f32_16x16x32_bf16 v[68:71], v[144:147], v[202:205], v[68:71]
	v_mfma_f32_16x16x32_bf16 v[64:67], v[152:155], v[202:205], v[64:67]
	v_mfma_f32_16x16x32_bf16 v[116:119], v[148:151], v[164:167], v[116:119]
	v_mfma_f32_16x16x32_bf16 v[108:111], v[156:159], v[164:167], v[108:111]
	v_mfma_f32_16x16x32_bf16 v[100:103], v[148:151], v[190:193], v[100:103]
	v_mfma_f32_16x16x32_bf16 v[92:95], v[156:159], v[190:193], v[92:95]
	v_mfma_f32_16x16x32_bf16 v[84:87], v[148:151], v[198:201], v[84:87]
	v_mfma_f32_16x16x32_bf16 v[76:79], v[156:159], v[198:201], v[76:79]
	v_mfma_f32_16x16x32_bf16 v[68:71], v[148:151], v[206:209], v[68:71]
	v_mfma_f32_16x16x32_bf16 v[64:67], v[156:159], v[206:209], v[64:67]
	s_setprio 0
	s_barrier
	s_add_i32 s38, s81, s91
	v_lshl_add_u64 v[210:211], s[96:97], 0, v[170:171]
	s_mov_b32 m0, s38
	ds_read_b128 v[160:163], v231 offset:16384
	ds_read_b128 v[164:167], v231 offset:17408
	ds_read_b128 v[186:189], v231 offset:18432
	ds_read_b128 v[190:193], v231 offset:19456
	ds_read_b128 v[194:197], v231 offset:20480
	ds_read_b128 v[198:201], v231 offset:21504
	ds_read_b128 v[202:205], v231 offset:22528
	ds_read_b128 v[206:209], v231 offset:23552
	global_load_lds_dwordx4 v[210:211], off
	s_add_i32 m0, s38, 0x2000
	s_add_u32 s38, s96, 0x100000
	v_lshl_add_u64 v[212:213], s[96:97], 0, v[174:175]
	s_addc_u32 s39, s97, 0
	s_add_i32 s40, s14, s91
	global_load_lds_dwordx4 v[212:213], off
	v_lshl_add_u64 v[214:215], s[38:39], 0, v[170:171]
	s_mov_b32 m0, s40
	v_lshl_add_u64 v[216:217], s[52:53], 0, v[172:173]
	global_load_lds_dwordx4 v[214:215], off
	v_lshl_add_u64 v[214:215], s[38:39], 0, v[174:175]
	s_add_i32 m0, s40, 0x2000
	s_nop 0
	global_load_lds_dwordx4 v[214:215], off
	v_lshl_add_u64 v[214:215], s[52:53], 0, v[168:169]
	s_waitcnt vmcnt(6)
	s_waitcnt lgkmcnt(0)
	s_barrier
	s_setprio 1
	s_waitcnt lgkmcnt(0)
	v_mfma_f32_16x16x32_bf16 v[60:63], v[128:131], v[160:163], v[60:63]
	v_mfma_f32_16x16x32_bf16 v[56:59], v[136:139], v[160:163], v[56:59]
	v_mfma_f32_16x16x32_bf16 v[44:47], v[128:131], v[186:189], v[44:47]
	v_mfma_f32_16x16x32_bf16 v[40:43], v[136:139], v[186:189], v[40:43]
	v_mfma_f32_16x16x32_bf16 v[28:31], v[128:131], v[194:197], v[28:31]
	v_mfma_f32_16x16x32_bf16 v[24:27], v[136:139], v[194:197], v[24:27]
	v_mfma_f32_16x16x32_bf16 v[12:15], v[128:131], v[202:205], v[12:15]
	v_mfma_f32_16x16x32_bf16 v[8:11], v[136:139], v[202:205], v[8:11]
	v_mfma_f32_16x16x32_bf16 v[60:63], v[132:135], v[164:167], v[60:63]
	v_mfma_f32_16x16x32_bf16 v[56:59], v[140:143], v[164:167], v[56:59]
	v_mfma_f32_16x16x32_bf16 v[44:47], v[132:135], v[190:193], v[44:47]
	v_mfma_f32_16x16x32_bf16 v[40:43], v[140:143], v[190:193], v[40:43]
	v_mfma_f32_16x16x32_bf16 v[28:31], v[132:135], v[198:201], v[28:31]
	v_mfma_f32_16x16x32_bf16 v[24:27], v[140:143], v[198:201], v[24:27]
	v_mfma_f32_16x16x32_bf16 v[12:15], v[132:135], v[206:209], v[12:15]
	v_mfma_f32_16x16x32_bf16 v[8:11], v[140:143], v[206:209], v[8:11]
	s_setprio 0
	s_setprio 1
	v_mfma_f32_16x16x32_bf16 v[52:55], v[144:147], v[160:163], v[52:55]
	v_mfma_f32_16x16x32_bf16 v[48:51], v[152:155], v[160:163], v[48:51]
	v_mfma_f32_16x16x32_bf16 v[36:39], v[144:147], v[186:189], v[36:39]
	v_mfma_f32_16x16x32_bf16 v[32:35], v[152:155], v[186:189], v[32:35]
	v_mfma_f32_16x16x32_bf16 v[20:23], v[144:147], v[194:197], v[20:23]
	v_mfma_f32_16x16x32_bf16 v[16:19], v[152:155], v[194:197], v[16:19]
	v_mfma_f32_16x16x32_bf16 v[4:7], v[144:147], v[202:205], v[4:7]
	v_mfma_f32_16x16x32_bf16 v[0:3], v[152:155], v[202:205], v[0:3]
	v_mfma_f32_16x16x32_bf16 v[52:55], v[148:151], v[164:167], v[52:55]
	v_mfma_f32_16x16x32_bf16 v[48:51], v[156:159], v[164:167], v[48:51]
	v_mfma_f32_16x16x32_bf16 v[36:39], v[148:151], v[190:193], v[36:39]
	v_mfma_f32_16x16x32_bf16 v[32:35], v[156:159], v[190:193], v[32:35]
	v_mfma_f32_16x16x32_bf16 v[20:23], v[148:151], v[198:201], v[20:23]
	v_mfma_f32_16x16x32_bf16 v[16:19], v[156:159], v[198:201], v[16:19]
	v_mfma_f32_16x16x32_bf16 v[4:7], v[148:151], v[206:209], v[4:7]
	v_mfma_f32_16x16x32_bf16 v[0:3], v[156:159], v[206:209], v[0:3]
	s_setprio 0
	s_barrier
	s_add_i32 s40, 0, 0x18000
	s_add_i32 s41, 0, 0x1c000
	v_add_u32_e32 v140, s40, v225
	v_add_u32_e32 v156, s41, v225
	ds_read_b128 v[128:131], v140
	ds_read_b128 v[132:135], v140 offset:1024
	ds_read_b128 v[136:139], v140 offset:2048
	ds_read_b128 v[140:143], v140 offset:3072
	ds_read_b128 v[144:147], v156
	ds_read_b128 v[148:151], v156 offset:1024
	ds_read_b128 v[152:155], v156 offset:2048
	ds_read_b128 v[156:159], v156 offset:3072
	s_add_u32 s38, s52, 0x100000
	s_addc_u32 s39, s53, 0
	s_mov_b32 m0, s17
	v_lshl_add_u64 v[218:219], s[38:39], 0, v[168:169]
	ds_read_b128 v[160:163], v231 offset:32768
	ds_read_b128 v[164:167], v231 offset:33792
	ds_read_b128 v[186:189], v231 offset:34816
	ds_read_b128 v[190:193], v231 offset:35840
	ds_read_b128 v[194:197], v231 offset:36864
	ds_read_b128 v[198:201], v231 offset:37888
	ds_read_b128 v[202:205], v231 offset:38912
	ds_read_b128 v[206:209], v231 offset:39936
	s_mov_b32 m0, s67
	s_nop 0
	global_load_lds_dwordx4 v[214:215], off
	s_mov_b32 m0, s16
	s_nop 0
	global_load_lds_dwordx4 v[216:217], off
	s_mov_b32 m0, s17
	s_nop 0
	global_load_lds_dwordx4 v[218:219], off
	v_lshl_add_u64 v[218:219], s[38:39], 0, v[172:173]
	s_mov_b32 m0, s10
	s_nop 0
	global_load_lds_dwordx4 v[218:219], off
	s_waitcnt vmcnt(8)
	s_waitcnt lgkmcnt(0)
	s_barrier
	s_setprio 1
	s_waitcnt lgkmcnt(0)
	v_mfma_f32_16x16x32_bf16 v[124:127], v[128:131], v[160:163], v[124:127]
	v_mfma_f32_16x16x32_bf16 v[120:123], v[136:139], v[160:163], v[120:123]
	v_mfma_f32_16x16x32_bf16 v[112:115], v[128:131], v[186:189], v[112:115]
	v_mfma_f32_16x16x32_bf16 v[104:107], v[136:139], v[186:189], v[104:107]
	v_mfma_f32_16x16x32_bf16 v[96:99], v[128:131], v[194:197], v[96:99]
	v_mfma_f32_16x16x32_bf16 v[88:91], v[136:139], v[194:197], v[88:91]
	v_mfma_f32_16x16x32_bf16 v[80:83], v[128:131], v[202:205], v[80:83]
	v_mfma_f32_16x16x32_bf16 v[72:75], v[136:139], v[202:205], v[72:75]
	v_mfma_f32_16x16x32_bf16 v[124:127], v[132:135], v[164:167], v[124:127]
	v_mfma_f32_16x16x32_bf16 v[120:123], v[140:143], v[164:167], v[120:123]
	v_mfma_f32_16x16x32_bf16 v[112:115], v[132:135], v[190:193], v[112:115]
	v_mfma_f32_16x16x32_bf16 v[104:107], v[140:143], v[190:193], v[104:107]
	v_mfma_f32_16x16x32_bf16 v[96:99], v[132:135], v[198:201], v[96:99]
	v_mfma_f32_16x16x32_bf16 v[88:91], v[140:143], v[198:201], v[88:91]
	v_mfma_f32_16x16x32_bf16 v[80:83], v[132:135], v[206:209], v[80:83]
	v_mfma_f32_16x16x32_bf16 v[72:75], v[140:143], v[206:209], v[72:75]
	s_setprio 0
	s_setprio 1
	v_mfma_f32_16x16x32_bf16 v[116:119], v[144:147], v[160:163], v[116:119]
	v_mfma_f32_16x16x32_bf16 v[108:111], v[152:155], v[160:163], v[108:111]
	v_mfma_f32_16x16x32_bf16 v[100:103], v[144:147], v[186:189], v[100:103]
	v_mfma_f32_16x16x32_bf16 v[92:95], v[152:155], v[186:189], v[92:95]
	v_mfma_f32_16x16x32_bf16 v[84:87], v[144:147], v[194:197], v[84:87]
	v_mfma_f32_16x16x32_bf16 v[76:79], v[152:155], v[194:197], v[76:79]
	v_mfma_f32_16x16x32_bf16 v[68:71], v[144:147], v[202:205], v[68:71]
	v_mfma_f32_16x16x32_bf16 v[64:67], v[152:155], v[202:205], v[64:67]
	v_mfma_f32_16x16x32_bf16 v[116:119], v[148:151], v[164:167], v[116:119]
	v_mfma_f32_16x16x32_bf16 v[108:111], v[156:159], v[164:167], v[108:111]
	v_mfma_f32_16x16x32_bf16 v[100:103], v[148:151], v[190:193], v[100:103]
	v_mfma_f32_16x16x32_bf16 v[92:95], v[156:159], v[190:193], v[92:95]
	v_mfma_f32_16x16x32_bf16 v[84:87], v[148:151], v[198:201], v[84:87]
	v_mfma_f32_16x16x32_bf16 v[76:79], v[156:159], v[198:201], v[76:79]
	v_mfma_f32_16x16x32_bf16 v[68:71], v[148:151], v[206:209], v[68:71]
	v_mfma_f32_16x16x32_bf16 v[64:67], v[156:159], v[206:209], v[64:67]
	s_setprio 0
	s_barrier
	s_add_i32 s38, s40, s91
	v_lshl_add_u64 v[210:211], v[210:211], 0, s[56:57]
	s_mov_b32 m0, s38
	ds_read_b128 v[160:163], v231 offset:49152
	ds_read_b128 v[164:167], v231 offset:50176
	ds_read_b128 v[186:189], v231 offset:51200
	ds_read_b128 v[190:193], v231 offset:52224
	ds_read_b128 v[194:197], v231 offset:53248
	ds_read_b128 v[198:201], v231 offset:54272
	ds_read_b128 v[202:205], v231 offset:55296
	ds_read_b128 v[206:209], v231 offset:56320
	global_load_lds_dwordx4 v[210:211], off
	s_add_i32 m0, s38, 0x2000
	s_add_u32 s38, s96, 0x100080
	v_lshl_add_u64 v[210:211], v[212:213], 0, s[56:57]
	s_addc_u32 s39, s97, 0
	s_add_i32 s40, s41, s91
	global_load_lds_dwordx4 v[210:211], off
	v_lshl_add_u64 v[210:211], s[38:39], 0, v[170:171]
	s_mov_b32 m0, s40
	s_nop 0
	global_load_lds_dwordx4 v[210:211], off
	v_lshl_add_u64 v[210:211], s[38:39], 0, v[174:175]
	s_add_i32 m0, s40, 0x2000
	s_nop 0
	global_load_lds_dwordx4 v[210:211], off
	v_lshl_add_u64 v[210:211], v[214:215], 0, s[56:57]
	s_mov_b32 m0, s13
	s_nop 0
	global_load_lds_dwordx4 v[210:211], off
	v_lshl_add_u64 v[210:211], v[216:217], 0, s[56:57]
	s_mov_b32 m0, s77
	s_nop 0
	global_load_lds_dwordx4 v[210:211], off
	s_waitcnt vmcnt(8)
	s_waitcnt lgkmcnt(0)
	s_barrier
	s_setprio 1
	s_waitcnt lgkmcnt(0)
	v_mfma_f32_16x16x32_bf16 v[60:63], v[128:131], v[160:163], v[60:63]
	v_mfma_f32_16x16x32_bf16 v[56:59], v[136:139], v[160:163], v[56:59]
	v_mfma_f32_16x16x32_bf16 v[44:47], v[128:131], v[186:189], v[44:47]
	v_mfma_f32_16x16x32_bf16 v[40:43], v[136:139], v[186:189], v[40:43]
	v_mfma_f32_16x16x32_bf16 v[28:31], v[128:131], v[194:197], v[28:31]
	v_mfma_f32_16x16x32_bf16 v[24:27], v[136:139], v[194:197], v[24:27]
	v_mfma_f32_16x16x32_bf16 v[12:15], v[128:131], v[202:205], v[12:15]
	v_mfma_f32_16x16x32_bf16 v[8:11], v[136:139], v[202:205], v[8:11]
	v_mfma_f32_16x16x32_bf16 v[60:63], v[132:135], v[164:167], v[60:63]
	v_mfma_f32_16x16x32_bf16 v[56:59], v[140:143], v[164:167], v[56:59]
	v_mfma_f32_16x16x32_bf16 v[44:47], v[132:135], v[190:193], v[44:47]
	v_mfma_f32_16x16x32_bf16 v[40:43], v[140:143], v[190:193], v[40:43]
	v_mfma_f32_16x16x32_bf16 v[28:31], v[132:135], v[198:201], v[28:31]
	v_mfma_f32_16x16x32_bf16 v[24:27], v[140:143], v[198:201], v[24:27]
	v_mfma_f32_16x16x32_bf16 v[12:15], v[132:135], v[206:209], v[12:15]
	v_mfma_f32_16x16x32_bf16 v[8:11], v[140:143], v[206:209], v[8:11]
	s_setprio 0
	s_setprio 1
	v_mfma_f32_16x16x32_bf16 v[52:55], v[144:147], v[160:163], v[52:55]
	v_mfma_f32_16x16x32_bf16 v[48:51], v[152:155], v[160:163], v[48:51]
	v_mfma_f32_16x16x32_bf16 v[36:39], v[144:147], v[186:189], v[36:39]
	v_mfma_f32_16x16x32_bf16 v[32:35], v[152:155], v[186:189], v[32:35]
	v_mfma_f32_16x16x32_bf16 v[20:23], v[144:147], v[194:197], v[20:23]
	v_mfma_f32_16x16x32_bf16 v[16:19], v[152:155], v[194:197], v[16:19]
	v_mfma_f32_16x16x32_bf16 v[4:7], v[144:147], v[202:205], v[4:7]
	v_mfma_f32_16x16x32_bf16 v[0:3], v[152:155], v[202:205], v[0:3]
	v_mfma_f32_16x16x32_bf16 v[52:55], v[148:151], v[164:167], v[52:55]
	v_mfma_f32_16x16x32_bf16 v[48:51], v[156:159], v[164:167], v[48:51]
	v_mfma_f32_16x16x32_bf16 v[36:39], v[148:151], v[190:193], v[36:39]
	v_mfma_f32_16x16x32_bf16 v[32:35], v[156:159], v[190:193], v[32:35]
	v_mfma_f32_16x16x32_bf16 v[20:23], v[148:151], v[198:201], v[20:23]
	v_mfma_f32_16x16x32_bf16 v[16:19], v[156:159], v[198:201], v[16:19]
	v_mfma_f32_16x16x32_bf16 v[4:7], v[148:151], v[206:209], v[4:7]
	v_mfma_f32_16x16x32_bf16 v[0:3], v[156:159], v[206:209], v[0:3]
	s_setprio 0
	s_barrier
	s_add_i32 s37, s37, 2
	s_add_u32 s35, s35, 0x100
	s_addc_u32 s36, s36, 0
	s_cmp_gt_u32 s37, 61
	s_mov_b64 s[94:95], vcc
	s_cbranch_scc0 .LBB0_116
	s_and_b64 vcc, exec, s[64:65]
	s_cbranch_vccz .LBB0_119
	s_barrier

.LBB0_521:
	ds_read_b128 v[152:155], v149
	ds_read_b128 v[156:159], v149 offset:1024
	ds_read_b128 v[160:163], v149 offset:2048
	ds_read_b128 v[164:167], v149 offset:3072
	ds_read_b128 v[168:171], v150
	ds_read_b128 v[172:175], v150 offset:1024
	ds_read_b128 v[176:179], v150 offset:2048
	ds_read_b128 v[180:183], v150 offset:3072
	s_add_u32 s37, s46, 0xfff80080
	s_addc_u32 s38, s47, -1
	s_cmp_eq_u32 s36, 28
	s_cselect_b32 s51, s13, s38
	s_cselect_b32 s50, s64, s37
	s_cselect_b32 s49, s11, s35
	s_cselect_b32 s48, s65, s34
	v_lshl_add_u64 v[144:145], s[46:47], 0, v[136:137]
	s_add_i32 m0, s17, 0xc000
	ds_read_b128 v[184:187], v151
	ds_read_b128 v[188:191], v151 offset:1024
	ds_read_b128 v[192:195], v151 offset:2048
	ds_read_b128 v[196:199], v151 offset:3072
	ds_read_b128 v[200:203], v151 offset:4096
	ds_read_b128 v[204:207], v151 offset:5120
	ds_read_b128 v[208:211], v151 offset:6144
	ds_read_b128 v[212:215], v151 offset:7168
	global_load_lds_dwordx4 v[144:145], off
	v_lshl_add_u64 v[144:145], s[46:47], 0, v[138:139]
	s_add_i32 m0, s17, 0xe000
	s_nop 0
	global_load_lds_dwordx4 v[144:145], off
	s_waitcnt vmcnt(8)
	s_waitcnt lgkmcnt(0)
	s_barrier
	s_setprio 1
	s_waitcnt lgkmcnt(0)
	v_mfma_f32_16x16x32_bf16 v[124:127], v[152:155], v[184:187], v[124:127]
	v_mfma_f32_16x16x32_bf16 v[120:123], v[160:163], v[184:187], v[120:123]
	v_mfma_f32_16x16x32_bf16 v[116:119], v[152:155], v[192:195], v[116:119]
	v_mfma_f32_16x16x32_bf16 v[108:111], v[160:163], v[192:195], v[108:111]
	v_mfma_f32_16x16x32_bf16 v[100:103], v[152:155], v[200:203], v[100:103]
	v_mfma_f32_16x16x32_bf16 v[92:95], v[160:163], v[200:203], v[92:95]
	v_mfma_f32_16x16x32_bf16 v[84:87], v[152:155], v[208:211], v[84:87]
	v_mfma_f32_16x16x32_bf16 v[76:79], v[160:163], v[208:211], v[76:79]
	v_mfma_f32_16x16x32_bf16 v[124:127], v[156:159], v[188:191], v[124:127]
	v_mfma_f32_16x16x32_bf16 v[120:123], v[164:167], v[188:191], v[120:123]
	v_mfma_f32_16x16x32_bf16 v[116:119], v[156:159], v[196:199], v[116:119]
	v_mfma_f32_16x16x32_bf16 v[108:111], v[164:167], v[196:199], v[108:111]
	v_mfma_f32_16x16x32_bf16 v[100:103], v[156:159], v[204:207], v[100:103]
	v_mfma_f32_16x16x32_bf16 v[92:95], v[164:167], v[204:207], v[92:95]
	v_mfma_f32_16x16x32_bf16 v[84:87], v[156:159], v[212:215], v[84:87]
	v_mfma_f32_16x16x32_bf16 v[76:79], v[164:167], v[212:215], v[76:79]
	s_setprio 0
	s_setprio 1
	v_mfma_f32_16x16x32_bf16 v[112:115], v[168:171], v[184:187], v[112:115]
	v_mfma_f32_16x16x32_bf16 v[104:107], v[176:179], v[184:187], v[104:107]
	v_mfma_f32_16x16x32_bf16 v[96:99], v[168:171], v[192:195], v[96:99]
	v_mfma_f32_16x16x32_bf16 v[88:91], v[176:179], v[192:195], v[88:91]
	v_mfma_f32_16x16x32_bf16 v[80:83], v[168:171], v[200:203], v[80:83]
	v_mfma_f32_16x16x32_bf16 v[72:75], v[176:179], v[200:203], v[72:75]
	v_mfma_f32_16x16x32_bf16 v[68:71], v[168:171], v[208:211], v[68:71]
	v_mfma_f32_16x16x32_bf16 v[64:67], v[176:179], v[208:211], v[64:67]
	v_mfma_f32_16x16x32_bf16 v[112:115], v[172:175], v[188:191], v[112:115]
	v_mfma_f32_16x16x32_bf16 v[104:107], v[180:183], v[188:191], v[104:107]
	v_mfma_f32_16x16x32_bf16 v[96:99], v[172:175], v[196:199], v[96:99]
	v_mfma_f32_16x16x32_bf16 v[88:91], v[180:183], v[196:199], v[88:91]
	v_mfma_f32_16x16x32_bf16 v[80:83], v[172:175], v[204:207], v[80:83]
	v_mfma_f32_16x16x32_bf16 v[72:75], v[180:183], v[204:207], v[72:75]
	v_mfma_f32_16x16x32_bf16 v[68:71], v[172:175], v[212:215], v[68:71]
	v_mfma_f32_16x16x32_bf16 v[64:67], v[180:183], v[212:215], v[64:67]
	s_setprio 0
	s_barrier
	s_add_i32 s37, s61, s53
	v_lshl_add_u64 v[144:145], s[48:49], 0, v[130:131]
	s_mov_b32 m0, s37
	ds_read_b128 v[184:187], v151 offset:16384
	ds_read_b128 v[188:191], v151 offset:17408
	ds_read_b128 v[192:195], v151 offset:18432
	ds_read_b128 v[196:199], v151 offset:19456
	ds_read_b128 v[200:203], v151 offset:20480
	ds_read_b128 v[204:207], v151 offset:21504
	ds_read_b128 v[208:211], v151 offset:22528
	ds_read_b128 v[212:215], v151 offset:23552
	global_load_lds_dwordx4 v[144:145], off
	s_add_i32 m0, s37, 0x2000
	s_add_u32 s38, s48, 0x80000
	v_lshl_add_u64 v[216:217], s[48:49], 0, v[134:135]
	s_addc_u32 s39, s49, 0
	s_add_i32 s37, s62, s53
	global_load_lds_dwordx4 v[216:217], off
	v_lshl_add_u64 v[218:219], s[38:39], 0, v[130:131]
	s_mov_b32 m0, s37
	v_lshl_add_u64 v[220:221], s[50:51], 0, v[132:133]
	global_load_lds_dwordx4 v[218:219], off
	v_lshl_add_u64 v[218:219], s[38:39], 0, v[134:135]
	s_add_i32 m0, s37, 0x2000
	s_nop 0
	global_load_lds_dwordx4 v[218:219], off
	v_lshl_add_u64 v[218:219], s[50:51], 0, v[128:129]
	s_waitcnt vmcnt(6)
	s_waitcnt lgkmcnt(0)
	s_barrier
	s_setprio 1
	s_waitcnt lgkmcnt(0)
	v_mfma_f32_16x16x32_bf16 v[60:63], v[152:155], v[184:187], v[60:63]
	v_mfma_f32_16x16x32_bf16 v[56:59], v[160:163], v[184:187], v[56:59]
	v_mfma_f32_16x16x32_bf16 v[52:55], v[152:155], v[192:195], v[52:55]
	v_mfma_f32_16x16x32_bf16 v[44:47], v[160:163], v[192:195], v[44:47]
	v_mfma_f32_16x16x32_bf16 v[36:39], v[152:155], v[200:203], v[36:39]
	v_mfma_f32_16x16x32_bf16 v[28:31], v[160:163], v[200:203], v[28:31]
	v_mfma_f32_16x16x32_bf16 v[20:23], v[152:155], v[208:211], v[20:23]
	v_mfma_f32_16x16x32_bf16 v[12:15], v[160:163], v[208:211], v[12:15]
	v_mfma_f32_16x16x32_bf16 v[60:63], v[156:159], v[188:191], v[60:63]
	v_mfma_f32_16x16x32_bf16 v[56:59], v[164:167], v[188:191], v[56:59]
	v_mfma_f32_16x16x32_bf16 v[52:55], v[156:159], v[196:199], v[52:55]
	v_mfma_f32_16x16x32_bf16 v[44:47], v[164:167], v[196:199], v[44:47]
	v_mfma_f32_16x16x32_bf16 v[36:39], v[156:159], v[204:207], v[36:39]
	v_mfma_f32_16x16x32_bf16 v[28:31], v[164:167], v[204:207], v[28:31]
	v_mfma_f32_16x16x32_bf16 v[20:23], v[156:159], v[212:215], v[20:23]
	v_mfma_f32_16x16x32_bf16 v[12:15], v[164:167], v[212:215], v[12:15]
	s_setprio 0
	s_setprio 1
	v_mfma_f32_16x16x32_bf16 v[48:51], v[168:171], v[184:187], v[48:51]
	v_mfma_f32_16x16x32_bf16 v[40:43], v[176:179], v[184:187], v[40:43]
	v_mfma_f32_16x16x32_bf16 v[32:35], v[168:171], v[192:195], v[32:35]
	v_mfma_f32_16x16x32_bf16 v[24:27], v[176:179], v[192:195], v[24:27]
	v_mfma_f32_16x16x32_bf16 v[16:19], v[168:171], v[200:203], v[16:19]
	v_mfma_f32_16x16x32_bf16 v[8:11], v[176:179], v[200:203], v[8:11]
	v_mfma_f32_16x16x32_bf16 v[4:7], v[168:171], v[208:211], v[4:7]
	v_mfma_f32_16x16x32_bf16 v[0:3], v[176:179], v[208:211], v[0:3]
	v_mfma_f32_16x16x32_bf16 v[48:51], v[172:175], v[188:191], v[48:51]
	v_mfma_f32_16x16x32_bf16 v[40:43], v[180:183], v[188:191], v[40:43]
	v_mfma_f32_16x16x32_bf16 v[32:35], v[172:175], v[196:199], v[32:35]
	v_mfma_f32_16x16x32_bf16 v[24:27], v[180:183], v[196:199], v[24:27]
	v_mfma_f32_16x16x32_bf16 v[16:19], v[172:175], v[204:207], v[16:19]
	v_mfma_f32_16x16x32_bf16 v[8:11], v[180:183], v[204:207], v[8:11]
	v_mfma_f32_16x16x32_bf16 v[4:7], v[172:175], v[212:215], v[4:7]
	v_mfma_f32_16x16x32_bf16 v[0:3], v[180:183], v[212:215], v[0:3]
	s_setprio 0
	s_barrier
	s_add_i32 s37, 0, 0x18000
	s_add_i32 s40, 0, 0x1c000
	v_add_u32_e32 v164, s37, v147
	v_add_u32_e32 v180, s40, v147
	ds_read_b128 v[152:155], v164
	ds_read_b128 v[156:159], v164 offset:1024
	ds_read_b128 v[160:163], v164 offset:2048
	ds_read_b128 v[164:167], v164 offset:3072
	ds_read_b128 v[168:171], v180
	ds_read_b128 v[172:175], v180 offset:1024
	ds_read_b128 v[176:179], v180 offset:2048
	ds_read_b128 v[180:183], v180 offset:3072
	s_add_u32 s38, s50, 0x80000
	s_addc_u32 s39, s51, 0
	s_mov_b32 m0, s55
	v_lshl_add_u64 v[222:223], s[38:39], 0, v[128:129]
	ds_read_b128 v[184:187], v151 offset:32768
	ds_read_b128 v[188:191], v151 offset:33792
	ds_read_b128 v[192:195], v151 offset:34816
	ds_read_b128 v[196:199], v151 offset:35840
	ds_read_b128 v[200:203], v151 offset:36864
	ds_read_b128 v[204:207], v151 offset:37888
	ds_read_b128 v[208:211], v151 offset:38912
	ds_read_b128 v[212:215], v151 offset:39936
	s_mov_b32 m0, s17
	s_nop 0
	global_load_lds_dwordx4 v[218:219], off
	s_mov_b32 m0, s54
	s_nop 0
	global_load_lds_dwordx4 v[220:221], off
	s_mov_b32 m0, s55
	s_nop 0
	global_load_lds_dwordx4 v[222:223], off
	v_lshl_add_u64 v[222:223], s[38:39], 0, v[132:133]
	s_mov_b32 m0, s56
	s_nop 0
	global_load_lds_dwordx4 v[222:223], off
	s_waitcnt vmcnt(8)
	s_waitcnt lgkmcnt(0)
	s_barrier
	s_setprio 1
	s_waitcnt lgkmcnt(0)
	v_mfma_f32_16x16x32_bf16 v[124:127], v[152:155], v[184:187], v[124:127]
	v_mfma_f32_16x16x32_bf16 v[120:123], v[160:163], v[184:187], v[120:123]
	v_mfma_f32_16x16x32_bf16 v[116:119], v[152:155], v[192:195], v[116:119]
	v_mfma_f32_16x16x32_bf16 v[108:111], v[160:163], v[192:195], v[108:111]
	v_mfma_f32_16x16x32_bf16 v[100:103], v[152:155], v[200:203], v[100:103]
	v_mfma_f32_16x16x32_bf16 v[92:95], v[160:163], v[200:203], v[92:95]
	v_mfma_f32_16x16x32_bf16 v[84:87], v[152:155], v[208:211], v[84:87]
	v_mfma_f32_16x16x32_bf16 v[76:79], v[160:163], v[208:211], v[76:79]
	v_mfma_f32_16x16x32_bf16 v[124:127], v[156:159], v[188:191], v[124:127]
	v_mfma_f32_16x16x32_bf16 v[120:123], v[164:167], v[188:191], v[120:123]
	v_mfma_f32_16x16x32_bf16 v[116:119], v[156:159], v[196:199], v[116:119]
	v_mfma_f32_16x16x32_bf16 v[108:111], v[164:167], v[196:199], v[108:111]
	v_mfma_f32_16x16x32_bf16 v[100:103], v[156:159], v[204:207], v[100:103]
	v_mfma_f32_16x16x32_bf16 v[92:95], v[164:167], v[204:207], v[92:95]
	v_mfma_f32_16x16x32_bf16 v[84:87], v[156:159], v[212:215], v[84:87]
	v_mfma_f32_16x16x32_bf16 v[76:79], v[164:167], v[212:215], v[76:79]
	s_setprio 0
	s_setprio 1
	v_mfma_f32_16x16x32_bf16 v[112:115], v[168:171], v[184:187], v[112:115]
	v_mfma_f32_16x16x32_bf16 v[104:107], v[176:179], v[184:187], v[104:107]
	v_mfma_f32_16x16x32_bf16 v[96:99], v[168:171], v[192:195], v[96:99]
	v_mfma_f32_16x16x32_bf16 v[88:91], v[176:179], v[192:195], v[88:91]
	v_mfma_f32_16x16x32_bf16 v[80:83], v[168:171], v[200:203], v[80:83]
	v_mfma_f32_16x16x32_bf16 v[72:75], v[176:179], v[200:203], v[72:75]
	v_mfma_f32_16x16x32_bf16 v[68:71], v[168:171], v[208:211], v[68:71]
	v_mfma_f32_16x16x32_bf16 v[64:67], v[176:179], v[208:211], v[64:67]
	v_mfma_f32_16x16x32_bf16 v[112:115], v[172:175], v[188:191], v[112:115]
	v_mfma_f32_16x16x32_bf16 v[104:107], v[180:183], v[188:191], v[104:107]
	v_mfma_f32_16x16x32_bf16 v[96:99], v[172:175], v[196:199], v[96:99]
	v_mfma_f32_16x16x32_bf16 v[88:91], v[180:183], v[196:199], v[88:91]
	v_mfma_f32_16x16x32_bf16 v[80:83], v[172:175], v[204:207], v[80:83]
	v_mfma_f32_16x16x32_bf16 v[72:75], v[180:183], v[204:207], v[72:75]
	v_mfma_f32_16x16x32_bf16 v[68:71], v[172:175], v[212:215], v[68:71]
	v_mfma_f32_16x16x32_bf16 v[64:67], v[180:183], v[212:215], v[64:67]
	s_setprio 0
	s_barrier
	s_add_i32 s37, s37, s53
	v_lshl_add_u64 v[144:145], v[144:145], 0, s[6:7]
	s_mov_b32 m0, s37
	ds_read_b128 v[184:187], v151 offset:49152
	ds_read_b128 v[188:191], v151 offset:50176
	ds_read_b128 v[192:195], v151 offset:51200
	ds_read_b128 v[196:199], v151 offset:52224
	ds_read_b128 v[200:203], v151 offset:53248
	ds_read_b128 v[204:207], v151 offset:54272
	ds_read_b128 v[208:211], v151 offset:55296
	ds_read_b128 v[212:215], v151 offset:56320
	global_load_lds_dwordx4 v[144:145], off
	s_add_i32 m0, s37, 0x2000
	s_add_u32 s38, s48, 0x80080
	v_lshl_add_u64 v[144:145], v[216:217], 0, s[6:7]
	s_addc_u32 s39, s49, 0
	s_add_i32 s37, s40, s53
	global_load_lds_dwordx4 v[144:145], off
	v_lshl_add_u64 v[144:145], s[38:39], 0, v[130:131]
	s_mov_b32 m0, s37
	s_nop 0
	global_load_lds_dwordx4 v[144:145], off
	v_lshl_add_u64 v[144:145], s[38:39], 0, v[134:135]
	s_add_i32 m0, s37, 0x2000
	s_nop 0
	global_load_lds_dwordx4 v[144:145], off
	v_lshl_add_u64 v[144:145], v[218:219], 0, s[6:7]
	s_mov_b32 m0, s58
	s_nop 0
	global_load_lds_dwordx4 v[144:145], off
	v_lshl_add_u64 v[144:145], v[220:221], 0, s[6:7]
	s_mov_b32 m0, s59
	s_nop 0
	global_load_lds_dwordx4 v[144:145], off
	s_waitcnt vmcnt(8)
	s_waitcnt lgkmcnt(0)
	s_barrier
	s_setprio 1
	s_waitcnt lgkmcnt(0)
	v_mfma_f32_16x16x32_bf16 v[60:63], v[152:155], v[184:187], v[60:63]
	v_mfma_f32_16x16x32_bf16 v[56:59], v[160:163], v[184:187], v[56:59]
	v_mfma_f32_16x16x32_bf16 v[52:55], v[152:155], v[192:195], v[52:55]
	v_mfma_f32_16x16x32_bf16 v[44:47], v[160:163], v[192:195], v[44:47]
	v_mfma_f32_16x16x32_bf16 v[36:39], v[152:155], v[200:203], v[36:39]
	v_mfma_f32_16x16x32_bf16 v[28:31], v[160:163], v[200:203], v[28:31]
	v_mfma_f32_16x16x32_bf16 v[20:23], v[152:155], v[208:211], v[20:23]
	v_mfma_f32_16x16x32_bf16 v[12:15], v[160:163], v[208:211], v[12:15]
	v_mfma_f32_16x16x32_bf16 v[60:63], v[156:159], v[188:191], v[60:63]
	v_mfma_f32_16x16x32_bf16 v[56:59], v[164:167], v[188:191], v[56:59]
	v_mfma_f32_16x16x32_bf16 v[52:55], v[156:159], v[196:199], v[52:55]
	v_mfma_f32_16x16x32_bf16 v[44:47], v[164:167], v[196:199], v[44:47]
	v_mfma_f32_16x16x32_bf16 v[36:39], v[156:159], v[204:207], v[36:39]
	v_mfma_f32_16x16x32_bf16 v[28:31], v[164:167], v[204:207], v[28:31]
	v_mfma_f32_16x16x32_bf16 v[20:23], v[156:159], v[212:215], v[20:23]
	v_mfma_f32_16x16x32_bf16 v[12:15], v[164:167], v[212:215], v[12:15]
	s_setprio 0
	s_setprio 1
	v_mfma_f32_16x16x32_bf16 v[48:51], v[168:171], v[184:187], v[48:51]
	v_mfma_f32_16x16x32_bf16 v[40:43], v[176:179], v[184:187], v[40:43]
	v_mfma_f32_16x16x32_bf16 v[32:35], v[168:171], v[192:195], v[32:35]
	v_mfma_f32_16x16x32_bf16 v[24:27], v[176:179], v[192:195], v[24:27]
	v_mfma_f32_16x16x32_bf16 v[16:19], v[168:171], v[200:203], v[16:19]
	v_mfma_f32_16x16x32_bf16 v[8:11], v[176:179], v[200:203], v[8:11]
	v_mfma_f32_16x16x32_bf16 v[4:7], v[168:171], v[208:211], v[4:7]
	v_mfma_f32_16x16x32_bf16 v[0:3], v[176:179], v[208:211], v[0:3]
	v_mfma_f32_16x16x32_bf16 v[48:51], v[172:175], v[188:191], v[48:51]
	v_mfma_f32_16x16x32_bf16 v[40:43], v[180:183], v[188:191], v[40:43]
	v_mfma_f32_16x16x32_bf16 v[32:35], v[172:175], v[196:199], v[32:35]
	v_mfma_f32_16x16x32_bf16 v[24:27], v[180:183], v[196:199], v[24:27]
	v_mfma_f32_16x16x32_bf16 v[16:19], v[172:175], v[204:207], v[16:19]
	v_mfma_f32_16x16x32_bf16 v[8:11], v[180:183], v[204:207], v[8:11]
	v_mfma_f32_16x16x32_bf16 v[4:7], v[172:175], v[212:215], v[4:7]
	v_mfma_f32_16x16x32_bf16 v[0:3], v[180:183], v[212:215], v[0:3]
	s_setprio 0
	s_barrier
	s_add_i32 s36, s36, 2
	s_add_u32 s46, s46, 0x100
	s_addc_u32 s47, s47, 0
	s_add_u32 s34, s34, 0x100
	s_addc_u32 s35, s35, 0
	s_cmp_gt_u32 s36, 29
	s_cbranch_scc0 .LBB0_521
	s_and_b64 vcc, exec, s[8:9]
	s_cbranch_vccz .LBB0_524
	s_barrier

.LBB0_600:
	ds_read_b128 v[152:155], v149
	ds_read_b128 v[156:159], v149 offset:1024
	ds_read_b128 v[160:163], v149 offset:2048
	ds_read_b128 v[164:167], v149 offset:3072
	ds_read_b128 v[168:171], v150
	ds_read_b128 v[172:175], v150 offset:1024
	ds_read_b128 v[176:179], v150 offset:2048
	ds_read_b128 v[180:183], v150 offset:3072
	s_add_u32 s37, s48, 0xfff00080
	s_addc_u32 s38, s49, -1
	s_cmp_eq_u32 s36, 60
	s_cselect_b32 s53, s17, s38
	s_cselect_b32 s52, s66, s37
	s_cselect_b32 s51, s13, s35
	s_cselect_b32 s50, s67, s34
	v_lshl_add_u64 v[144:145], s[48:49], 0, v[136:137]
	s_add_i32 m0, s19, 0xc000
	ds_read_b128 v[184:187], v151
	ds_read_b128 v[188:191], v151 offset:1024
	ds_read_b128 v[192:195], v151 offset:2048
	ds_read_b128 v[196:199], v151 offset:3072
	ds_read_b128 v[200:203], v151 offset:4096
	ds_read_b128 v[204:207], v151 offset:5120
	ds_read_b128 v[208:211], v151 offset:6144
	ds_read_b128 v[212:215], v151 offset:7168
	global_load_lds_dwordx4 v[144:145], off
	v_lshl_add_u64 v[144:145], s[48:49], 0, v[138:139]
	s_add_i32 m0, s19, 0xe000
	s_nop 0
	global_load_lds_dwordx4 v[144:145], off
	s_waitcnt vmcnt(8)
	s_waitcnt lgkmcnt(0)
	s_barrier
	s_setprio 1
	s_waitcnt lgkmcnt(0)
	v_mfma_f32_16x16x32_bf16 v[124:127], v[152:155], v[184:187], v[124:127]
	v_mfma_f32_16x16x32_bf16 v[120:123], v[160:163], v[184:187], v[120:123]
	v_mfma_f32_16x16x32_bf16 v[116:119], v[152:155], v[192:195], v[116:119]
	v_mfma_f32_16x16x32_bf16 v[108:111], v[160:163], v[192:195], v[108:111]
	v_mfma_f32_16x16x32_bf16 v[100:103], v[152:155], v[200:203], v[100:103]
	v_mfma_f32_16x16x32_bf16 v[92:95], v[160:163], v[200:203], v[92:95]
	v_mfma_f32_16x16x32_bf16 v[84:87], v[152:155], v[208:211], v[84:87]
	v_mfma_f32_16x16x32_bf16 v[76:79], v[160:163], v[208:211], v[76:79]
	v_mfma_f32_16x16x32_bf16 v[124:127], v[156:159], v[188:191], v[124:127]
	v_mfma_f32_16x16x32_bf16 v[120:123], v[164:167], v[188:191], v[120:123]
	v_mfma_f32_16x16x32_bf16 v[116:119], v[156:159], v[196:199], v[116:119]
	v_mfma_f32_16x16x32_bf16 v[108:111], v[164:167], v[196:199], v[108:111]
	v_mfma_f32_16x16x32_bf16 v[100:103], v[156:159], v[204:207], v[100:103]
	v_mfma_f32_16x16x32_bf16 v[92:95], v[164:167], v[204:207], v[92:95]
	v_mfma_f32_16x16x32_bf16 v[84:87], v[156:159], v[212:215], v[84:87]
	v_mfma_f32_16x16x32_bf16 v[76:79], v[164:167], v[212:215], v[76:79]
	s_setprio 0
	s_setprio 1
	v_mfma_f32_16x16x32_bf16 v[112:115], v[168:171], v[184:187], v[112:115]
	v_mfma_f32_16x16x32_bf16 v[104:107], v[176:179], v[184:187], v[104:107]
	v_mfma_f32_16x16x32_bf16 v[96:99], v[168:171], v[192:195], v[96:99]
	v_mfma_f32_16x16x32_bf16 v[88:91], v[176:179], v[192:195], v[88:91]
	v_mfma_f32_16x16x32_bf16 v[80:83], v[168:171], v[200:203], v[80:83]
	v_mfma_f32_16x16x32_bf16 v[72:75], v[176:179], v[200:203], v[72:75]
	v_mfma_f32_16x16x32_bf16 v[68:71], v[168:171], v[208:211], v[68:71]
	v_mfma_f32_16x16x32_bf16 v[64:67], v[176:179], v[208:211], v[64:67]
	v_mfma_f32_16x16x32_bf16 v[112:115], v[172:175], v[188:191], v[112:115]
	v_mfma_f32_16x16x32_bf16 v[104:107], v[180:183], v[188:191], v[104:107]
	v_mfma_f32_16x16x32_bf16 v[96:99], v[172:175], v[196:199], v[96:99]
	v_mfma_f32_16x16x32_bf16 v[88:91], v[180:183], v[196:199], v[88:91]
	v_mfma_f32_16x16x32_bf16 v[80:83], v[172:175], v[204:207], v[80:83]
	v_mfma_f32_16x16x32_bf16 v[72:75], v[180:183], v[204:207], v[72:75]
	v_mfma_f32_16x16x32_bf16 v[68:71], v[172:175], v[212:215], v[68:71]
	v_mfma_f32_16x16x32_bf16 v[64:67], v[180:183], v[212:215], v[64:67]
	s_setprio 0
	s_barrier
	s_add_i32 s37, s63, s55
	v_lshl_add_u64 v[144:145], s[50:51], 0, v[130:131]
	s_mov_b32 m0, s37
	ds_read_b128 v[184:187], v151 offset:16384
	ds_read_b128 v[188:191], v151 offset:17408
	ds_read_b128 v[192:195], v151 offset:18432
	ds_read_b128 v[196:199], v151 offset:19456
	ds_read_b128 v[200:203], v151 offset:20480
	ds_read_b128 v[204:207], v151 offset:21504
	ds_read_b128 v[208:211], v151 offset:22528
	ds_read_b128 v[212:215], v151 offset:23552
	global_load_lds_dwordx4 v[144:145], off
	s_add_i32 m0, s37, 0x2000
	s_add_u32 s38, s50, 0x100000
	v_lshl_add_u64 v[216:217], s[50:51], 0, v[134:135]
	s_addc_u32 s39, s51, 0
	s_add_i32 s37, s64, s55
	global_load_lds_dwordx4 v[216:217], off
	v_lshl_add_u64 v[218:219], s[38:39], 0, v[130:131]
	s_mov_b32 m0, s37
	v_lshl_add_u64 v[220:221], s[52:53], 0, v[132:133]
	global_load_lds_dwordx4 v[218:219], off
	v_lshl_add_u64 v[218:219], s[38:39], 0, v[134:135]
	s_add_i32 m0, s37, 0x2000
	s_nop 0
	global_load_lds_dwordx4 v[218:219], off
	v_lshl_add_u64 v[218:219], s[52:53], 0, v[128:129]
	s_waitcnt vmcnt(6)
	s_waitcnt lgkmcnt(0)
	s_barrier
	s_setprio 1
	s_waitcnt lgkmcnt(0)
	v_mfma_f32_16x16x32_bf16 v[60:63], v[152:155], v[184:187], v[60:63]
	v_mfma_f32_16x16x32_bf16 v[56:59], v[160:163], v[184:187], v[56:59]
	v_mfma_f32_16x16x32_bf16 v[52:55], v[152:155], v[192:195], v[52:55]
	v_mfma_f32_16x16x32_bf16 v[44:47], v[160:163], v[192:195], v[44:47]
	v_mfma_f32_16x16x32_bf16 v[36:39], v[152:155], v[200:203], v[36:39]
	v_mfma_f32_16x16x32_bf16 v[28:31], v[160:163], v[200:203], v[28:31]
	v_mfma_f32_16x16x32_bf16 v[20:23], v[152:155], v[208:211], v[20:23]
	v_mfma_f32_16x16x32_bf16 v[12:15], v[160:163], v[208:211], v[12:15]
	v_mfma_f32_16x16x32_bf16 v[60:63], v[156:159], v[188:191], v[60:63]
	v_mfma_f32_16x16x32_bf16 v[56:59], v[164:167], v[188:191], v[56:59]
	v_mfma_f32_16x16x32_bf16 v[52:55], v[156:159], v[196:199], v[52:55]
	v_mfma_f32_16x16x32_bf16 v[44:47], v[164:167], v[196:199], v[44:47]
	v_mfma_f32_16x16x32_bf16 v[36:39], v[156:159], v[204:207], v[36:39]
	v_mfma_f32_16x16x32_bf16 v[28:31], v[164:167], v[204:207], v[28:31]
	v_mfma_f32_16x16x32_bf16 v[20:23], v[156:159], v[212:215], v[20:23]
	v_mfma_f32_16x16x32_bf16 v[12:15], v[164:167], v[212:215], v[12:15]
	s_setprio 0
	s_setprio 1
	v_mfma_f32_16x16x32_bf16 v[48:51], v[168:171], v[184:187], v[48:51]
	v_mfma_f32_16x16x32_bf16 v[40:43], v[176:179], v[184:187], v[40:43]
	v_mfma_f32_16x16x32_bf16 v[32:35], v[168:171], v[192:195], v[32:35]
	v_mfma_f32_16x16x32_bf16 v[24:27], v[176:179], v[192:195], v[24:27]
	v_mfma_f32_16x16x32_bf16 v[16:19], v[168:171], v[200:203], v[16:19]
	v_mfma_f32_16x16x32_bf16 v[8:11], v[176:179], v[200:203], v[8:11]
	v_mfma_f32_16x16x32_bf16 v[4:7], v[168:171], v[208:211], v[4:7]
	v_mfma_f32_16x16x32_bf16 v[0:3], v[176:179], v[208:211], v[0:3]
	v_mfma_f32_16x16x32_bf16 v[48:51], v[172:175], v[188:191], v[48:51]
	v_mfma_f32_16x16x32_bf16 v[40:43], v[180:183], v[188:191], v[40:43]
	v_mfma_f32_16x16x32_bf16 v[32:35], v[172:175], v[196:199], v[32:35]
	v_mfma_f32_16x16x32_bf16 v[24:27], v[180:183], v[196:199], v[24:27]
	v_mfma_f32_16x16x32_bf16 v[16:19], v[172:175], v[204:207], v[16:19]
	v_mfma_f32_16x16x32_bf16 v[8:11], v[180:183], v[204:207], v[8:11]
	v_mfma_f32_16x16x32_bf16 v[4:7], v[172:175], v[212:215], v[4:7]
	v_mfma_f32_16x16x32_bf16 v[0:3], v[180:183], v[212:215], v[0:3]
	s_setprio 0
	s_barrier
	s_add_i32 s37, 0, 0x18000
	s_add_i32 s40, 0, 0x1c000
	v_add_u32_e32 v164, s37, v147
	v_add_u32_e32 v180, s40, v147
	ds_read_b128 v[152:155], v164
	ds_read_b128 v[156:159], v164 offset:1024
	ds_read_b128 v[160:163], v164 offset:2048
	ds_read_b128 v[164:167], v164 offset:3072
	ds_read_b128 v[168:171], v180
	ds_read_b128 v[172:175], v180 offset:1024
	ds_read_b128 v[176:179], v180 offset:2048
	ds_read_b128 v[180:183], v180 offset:3072
	s_add_u32 s38, s52, 0x100000
	s_addc_u32 s39, s53, 0
	s_mov_b32 m0, s57
	v_lshl_add_u64 v[222:223], s[38:39], 0, v[128:129]
	ds_read_b128 v[184:187], v151 offset:32768
	ds_read_b128 v[188:191], v151 offset:33792
	ds_read_b128 v[192:195], v151 offset:34816
	ds_read_b128 v[196:199], v151 offset:35840
	ds_read_b128 v[200:203], v151 offset:36864
	ds_read_b128 v[204:207], v151 offset:37888
	ds_read_b128 v[208:211], v151 offset:38912
	ds_read_b128 v[212:215], v151 offset:39936
	s_mov_b32 m0, s19
	s_nop 0
	global_load_lds_dwordx4 v[218:219], off
	s_mov_b32 m0, s56
	s_nop 0
	global_load_lds_dwordx4 v[220:221], off
	s_mov_b32 m0, s57
	s_nop 0
	global_load_lds_dwordx4 v[222:223], off
	v_lshl_add_u64 v[222:223], s[38:39], 0, v[132:133]
	s_mov_b32 m0, s58
	s_nop 0
	global_load_lds_dwordx4 v[222:223], off
	s_waitcnt vmcnt(8)
	s_waitcnt lgkmcnt(0)
	s_barrier
	s_setprio 1
	s_waitcnt lgkmcnt(0)
	v_mfma_f32_16x16x32_bf16 v[124:127], v[152:155], v[184:187], v[124:127]
	v_mfma_f32_16x16x32_bf16 v[120:123], v[160:163], v[184:187], v[120:123]
	v_mfma_f32_16x16x32_bf16 v[116:119], v[152:155], v[192:195], v[116:119]
	v_mfma_f32_16x16x32_bf16 v[108:111], v[160:163], v[192:195], v[108:111]
	v_mfma_f32_16x16x32_bf16 v[100:103], v[152:155], v[200:203], v[100:103]
	v_mfma_f32_16x16x32_bf16 v[92:95], v[160:163], v[200:203], v[92:95]
	v_mfma_f32_16x16x32_bf16 v[84:87], v[152:155], v[208:211], v[84:87]
	v_mfma_f32_16x16x32_bf16 v[76:79], v[160:163], v[208:211], v[76:79]
	v_mfma_f32_16x16x32_bf16 v[124:127], v[156:159], v[188:191], v[124:127]
	v_mfma_f32_16x16x32_bf16 v[120:123], v[164:167], v[188:191], v[120:123]
	v_mfma_f32_16x16x32_bf16 v[116:119], v[156:159], v[196:199], v[116:119]
	v_mfma_f32_16x16x32_bf16 v[108:111], v[164:167], v[196:199], v[108:111]
	v_mfma_f32_16x16x32_bf16 v[100:103], v[156:159], v[204:207], v[100:103]
	v_mfma_f32_16x16x32_bf16 v[92:95], v[164:167], v[204:207], v[92:95]
	v_mfma_f32_16x16x32_bf16 v[84:87], v[156:159], v[212:215], v[84:87]
	v_mfma_f32_16x16x32_bf16 v[76:79], v[164:167], v[212:215], v[76:79]
	s_setprio 0
	s_setprio 1
	v_mfma_f32_16x16x32_bf16 v[112:115], v[168:171], v[184:187], v[112:115]
	v_mfma_f32_16x16x32_bf16 v[104:107], v[176:179], v[184:187], v[104:107]
	v_mfma_f32_16x16x32_bf16 v[96:99], v[168:171], v[192:195], v[96:99]
	v_mfma_f32_16x16x32_bf16 v[88:91], v[176:179], v[192:195], v[88:91]
	v_mfma_f32_16x16x32_bf16 v[80:83], v[168:171], v[200:203], v[80:83]
	v_mfma_f32_16x16x32_bf16 v[72:75], v[176:179], v[200:203], v[72:75]
	v_mfma_f32_16x16x32_bf16 v[68:71], v[168:171], v[208:211], v[68:71]
	v_mfma_f32_16x16x32_bf16 v[64:67], v[176:179], v[208:211], v[64:67]
	v_mfma_f32_16x16x32_bf16 v[112:115], v[172:175], v[188:191], v[112:115]
	v_mfma_f32_16x16x32_bf16 v[104:107], v[180:183], v[188:191], v[104:107]
	v_mfma_f32_16x16x32_bf16 v[96:99], v[172:175], v[196:199], v[96:99]
	v_mfma_f32_16x16x32_bf16 v[88:91], v[180:183], v[196:199], v[88:91]
	v_mfma_f32_16x16x32_bf16 v[80:83], v[172:175], v[204:207], v[80:83]
	v_mfma_f32_16x16x32_bf16 v[72:75], v[180:183], v[204:207], v[72:75]
	v_mfma_f32_16x16x32_bf16 v[68:71], v[172:175], v[212:215], v[68:71]
	v_mfma_f32_16x16x32_bf16 v[64:67], v[180:183], v[212:215], v[64:67]
	s_setprio 0
	s_barrier
	s_add_i32 s37, s37, s55
	v_lshl_add_u64 v[144:145], v[144:145], 0, s[8:9]
	s_mov_b32 m0, s37
	ds_read_b128 v[184:187], v151 offset:49152
	ds_read_b128 v[188:191], v151 offset:50176
	ds_read_b128 v[192:195], v151 offset:51200
	ds_read_b128 v[196:199], v151 offset:52224
	ds_read_b128 v[200:203], v151 offset:53248
	ds_read_b128 v[204:207], v151 offset:54272
	ds_read_b128 v[208:211], v151 offset:55296
	ds_read_b128 v[212:215], v151 offset:56320
	global_load_lds_dwordx4 v[144:145], off
	s_add_i32 m0, s37, 0x2000
	s_add_u32 s38, s50, 0x100080
	v_lshl_add_u64 v[144:145], v[216:217], 0, s[8:9]
	s_addc_u32 s39, s51, 0
	s_add_i32 s37, s40, s55
	global_load_lds_dwordx4 v[144:145], off
	v_lshl_add_u64 v[144:145], s[38:39], 0, v[130:131]
	s_mov_b32 m0, s37
	s_nop 0
	global_load_lds_dwordx4 v[144:145], off
	v_lshl_add_u64 v[144:145], s[38:39], 0, v[134:135]
	s_add_i32 m0, s37, 0x2000
	s_nop 0
	global_load_lds_dwordx4 v[144:145], off
	v_lshl_add_u64 v[144:145], v[218:219], 0, s[8:9]
	s_mov_b32 m0, s60
	s_nop 0
	global_load_lds_dwordx4 v[144:145], off
	v_lshl_add_u64 v[144:145], v[220:221], 0, s[8:9]
	s_mov_b32 m0, s61
	s_nop 0
	global_load_lds_dwordx4 v[144:145], off
	s_waitcnt vmcnt(8)
	s_waitcnt lgkmcnt(0)
	s_barrier
	s_setprio 1
	s_waitcnt lgkmcnt(0)
	v_mfma_f32_16x16x32_bf16 v[60:63], v[152:155], v[184:187], v[60:63]
	v_mfma_f32_16x16x32_bf16 v[56:59], v[160:163], v[184:187], v[56:59]
	v_mfma_f32_16x16x32_bf16 v[52:55], v[152:155], v[192:195], v[52:55]
	v_mfma_f32_16x16x32_bf16 v[44:47], v[160:163], v[192:195], v[44:47]
	v_mfma_f32_16x16x32_bf16 v[36:39], v[152:155], v[200:203], v[36:39]
	v_mfma_f32_16x16x32_bf16 v[28:31], v[160:163], v[200:203], v[28:31]
	v_mfma_f32_16x16x32_bf16 v[20:23], v[152:155], v[208:211], v[20:23]
	v_mfma_f32_16x16x32_bf16 v[12:15], v[160:163], v[208:211], v[12:15]
	v_mfma_f32_16x16x32_bf16 v[60:63], v[156:159], v[188:191], v[60:63]
	v_mfma_f32_16x16x32_bf16 v[56:59], v[164:167], v[188:191], v[56:59]
	v_mfma_f32_16x16x32_bf16 v[52:55], v[156:159], v[196:199], v[52:55]
	v_mfma_f32_16x16x32_bf16 v[44:47], v[164:167], v[196:199], v[44:47]
	v_mfma_f32_16x16x32_bf16 v[36:39], v[156:159], v[204:207], v[36:39]
	v_mfma_f32_16x16x32_bf16 v[28:31], v[164:167], v[204:207], v[28:31]
	v_mfma_f32_16x16x32_bf16 v[20:23], v[156:159], v[212:215], v[20:23]
	v_mfma_f32_16x16x32_bf16 v[12:15], v[164:167], v[212:215], v[12:15]
	s_setprio 0
	s_setprio 1
	v_mfma_f32_16x16x32_bf16 v[48:51], v[168:171], v[184:187], v[48:51]
	v_mfma_f32_16x16x32_bf16 v[40:43], v[176:179], v[184:187], v[40:43]
	v_mfma_f32_16x16x32_bf16 v[32:35], v[168:171], v[192:195], v[32:35]
	v_mfma_f32_16x16x32_bf16 v[24:27], v[176:179], v[192:195], v[24:27]
	v_mfma_f32_16x16x32_bf16 v[16:19], v[168:171], v[200:203], v[16:19]
	v_mfma_f32_16x16x32_bf16 v[8:11], v[176:179], v[200:203], v[8:11]
	v_mfma_f32_16x16x32_bf16 v[4:7], v[168:171], v[208:211], v[4:7]
	v_mfma_f32_16x16x32_bf16 v[0:3], v[176:179], v[208:211], v[0:3]
	v_mfma_f32_16x16x32_bf16 v[48:51], v[172:175], v[188:191], v[48:51]
	v_mfma_f32_16x16x32_bf16 v[40:43], v[180:183], v[188:191], v[40:43]
	v_mfma_f32_16x16x32_bf16 v[32:35], v[172:175], v[196:199], v[32:35]
	v_mfma_f32_16x16x32_bf16 v[24:27], v[180:183], v[196:199], v[24:27]
	v_mfma_f32_16x16x32_bf16 v[16:19], v[172:175], v[204:207], v[16:19]
	v_mfma_f32_16x16x32_bf16 v[8:11], v[180:183], v[204:207], v[8:11]
	v_mfma_f32_16x16x32_bf16 v[4:7], v[172:175], v[212:215], v[4:7]
	v_mfma_f32_16x16x32_bf16 v[0:3], v[180:183], v[212:215], v[0:3]
	s_setprio 0
	s_barrier
	s_add_i32 s36, s36, 2
	s_add_u32 s48, s48, 0x100
	s_addc_u32 s49, s49, 0
	s_add_u32 s34, s34, 0x100
	s_addc_u32 s35, s35, 0
	s_cmp_gt_u32 s36, 61
	s_cbranch_scc0 .LBB0_600
	s_and_b64 vcc, exec, s[10:11]
	s_cbranch_vccz .LBB0_603
	s_barrier

.LBB0_679:
	ds_read_b128 v[144:147], v151
	ds_read_b128 v[154:157], v151 offset:1024
	ds_read_b128 v[158:161], v151 offset:2048
	ds_read_b128 v[162:165], v151 offset:3072
	ds_read_b128 v[166:169], v152
	ds_read_b128 v[170:173], v152 offset:1024
	ds_read_b128 v[174:177], v152 offset:2048
	ds_read_b128 v[178:181], v152 offset:3072
	s_add_u32 s37, s50, 0xfff00080
	s_addc_u32 s38, s51, -1
	s_cmp_eq_u32 s36, 60
	s_cselect_b32 s55, s19, s38
	s_cselect_b32 s54, s66, s37
	s_cselect_b32 s53, s17, s35
	s_cselect_b32 s52, s67, s34
	v_lshl_add_u64 v[214:215], s[50:51], 0, v[136:137]
	s_add_i32 m0, s49, 0xc000
	ds_read_b128 v[182:185], v153
	ds_read_b128 v[186:189], v153 offset:1024
	ds_read_b128 v[190:193], v153 offset:2048
	ds_read_b128 v[194:197], v153 offset:3072
	ds_read_b128 v[198:201], v153 offset:4096
	ds_read_b128 v[202:205], v153 offset:5120
	ds_read_b128 v[206:209], v153 offset:6144
	ds_read_b128 v[210:213], v153 offset:7168
	global_load_lds_dwordx4 v[214:215], off
	v_lshl_add_u64 v[214:215], s[50:51], 0, v[138:139]
	s_add_i32 m0, s49, 0xe000
	s_nop 0
	global_load_lds_dwordx4 v[214:215], off
	s_waitcnt vmcnt(8)
	s_waitcnt lgkmcnt(0)
	s_barrier
	s_setprio 1
	s_waitcnt lgkmcnt(0)
	v_mfma_f32_16x16x32_bf16 v[124:127], v[144:147], v[182:185], v[124:127]
	v_mfma_f32_16x16x32_bf16 v[116:119], v[158:161], v[182:185], v[116:119]
	v_mfma_f32_16x16x32_bf16 v[108:111], v[144:147], v[190:193], v[108:111]
	v_mfma_f32_16x16x32_bf16 v[104:107], v[158:161], v[190:193], v[104:107]
	v_mfma_f32_16x16x32_bf16 v[92:95], v[144:147], v[198:201], v[92:95]
	v_mfma_f32_16x16x32_bf16 v[88:91], v[158:161], v[198:201], v[88:91]
	v_mfma_f32_16x16x32_bf16 v[76:79], v[144:147], v[206:209], v[76:79]
	v_mfma_f32_16x16x32_bf16 v[72:75], v[158:161], v[206:209], v[72:75]
	v_mfma_f32_16x16x32_bf16 v[124:127], v[154:157], v[186:189], v[124:127]
	v_mfma_f32_16x16x32_bf16 v[116:119], v[162:165], v[186:189], v[116:119]
	v_mfma_f32_16x16x32_bf16 v[108:111], v[154:157], v[194:197], v[108:111]
	v_mfma_f32_16x16x32_bf16 v[104:107], v[162:165], v[194:197], v[104:107]
	v_mfma_f32_16x16x32_bf16 v[92:95], v[154:157], v[202:205], v[92:95]
	v_mfma_f32_16x16x32_bf16 v[88:91], v[162:165], v[202:205], v[88:91]
	v_mfma_f32_16x16x32_bf16 v[76:79], v[154:157], v[210:213], v[76:79]
	v_mfma_f32_16x16x32_bf16 v[72:75], v[162:165], v[210:213], v[72:75]
	s_setprio 0
	s_setprio 1
	v_mfma_f32_16x16x32_bf16 v[120:123], v[166:169], v[182:185], v[120:123]
	v_mfma_f32_16x16x32_bf16 v[112:115], v[174:177], v[182:185], v[112:115]
	v_mfma_f32_16x16x32_bf16 v[100:103], v[166:169], v[190:193], v[100:103]
	v_mfma_f32_16x16x32_bf16 v[96:99], v[174:177], v[190:193], v[96:99]
	v_mfma_f32_16x16x32_bf16 v[84:87], v[166:169], v[198:201], v[84:87]
	v_mfma_f32_16x16x32_bf16 v[80:83], v[174:177], v[198:201], v[80:83]
	v_mfma_f32_16x16x32_bf16 v[68:71], v[166:169], v[206:209], v[68:71]
	v_mfma_f32_16x16x32_bf16 v[64:67], v[174:177], v[206:209], v[64:67]
	v_mfma_f32_16x16x32_bf16 v[120:123], v[170:173], v[186:189], v[120:123]
	v_mfma_f32_16x16x32_bf16 v[112:115], v[178:181], v[186:189], v[112:115]
	v_mfma_f32_16x16x32_bf16 v[100:103], v[170:173], v[194:197], v[100:103]
	v_mfma_f32_16x16x32_bf16 v[96:99], v[178:181], v[194:197], v[96:99]
	v_mfma_f32_16x16x32_bf16 v[84:87], v[170:173], v[202:205], v[84:87]
	v_mfma_f32_16x16x32_bf16 v[80:83], v[178:181], v[202:205], v[80:83]
	v_mfma_f32_16x16x32_bf16 v[68:71], v[170:173], v[210:213], v[68:71]
	v_mfma_f32_16x16x32_bf16 v[64:67], v[178:181], v[210:213], v[64:67]
	s_setprio 0
	s_barrier
	s_add_i32 s37, s63, s33
	v_lshl_add_u64 v[214:215], s[52:53], 0, v[130:131]
	s_mov_b32 m0, s37
	ds_read_b128 v[182:185], v153 offset:16384
	ds_read_b128 v[186:189], v153 offset:17408
	ds_read_b128 v[190:193], v153 offset:18432
	ds_read_b128 v[194:197], v153 offset:19456
	ds_read_b128 v[198:201], v153 offset:20480
	ds_read_b128 v[202:205], v153 offset:21504
	ds_read_b128 v[206:209], v153 offset:22528
	ds_read_b128 v[210:213], v153 offset:23552
	global_load_lds_dwordx4 v[214:215], off
	s_add_i32 m0, s37, 0x2000
	s_add_u32 s38, s52, 0x100000
	v_lshl_add_u64 v[216:217], s[52:53], 0, v[134:135]
	s_addc_u32 s39, s53, 0
	s_add_i32 s37, s64, s33
	global_load_lds_dwordx4 v[216:217], off
	v_lshl_add_u64 v[218:219], s[38:39], 0, v[130:131]
	s_mov_b32 m0, s37
	v_lshl_add_u64 v[220:221], s[54:55], 0, v[132:133]
	global_load_lds_dwordx4 v[218:219], off
	v_lshl_add_u64 v[218:219], s[38:39], 0, v[134:135]
	s_add_i32 m0, s37, 0x2000
	s_nop 0
	global_load_lds_dwordx4 v[218:219], off
	v_lshl_add_u64 v[218:219], s[54:55], 0, v[128:129]
	s_waitcnt vmcnt(6)
	s_waitcnt lgkmcnt(0)
	s_barrier
	s_setprio 1
	s_waitcnt lgkmcnt(0)
	v_mfma_f32_16x16x32_bf16 v[60:63], v[144:147], v[182:185], v[60:63]
	v_mfma_f32_16x16x32_bf16 v[56:59], v[158:161], v[182:185], v[56:59]
	v_mfma_f32_16x16x32_bf16 v[44:47], v[144:147], v[190:193], v[44:47]
	v_mfma_f32_16x16x32_bf16 v[40:43], v[158:161], v[190:193], v[40:43]
	v_mfma_f32_16x16x32_bf16 v[28:31], v[144:147], v[198:201], v[28:31]
	v_mfma_f32_16x16x32_bf16 v[24:27], v[158:161], v[198:201], v[24:27]
	v_mfma_f32_16x16x32_bf16 v[12:15], v[144:147], v[206:209], v[12:15]
	v_mfma_f32_16x16x32_bf16 v[8:11], v[158:161], v[206:209], v[8:11]
	v_mfma_f32_16x16x32_bf16 v[60:63], v[154:157], v[186:189], v[60:63]
	v_mfma_f32_16x16x32_bf16 v[56:59], v[162:165], v[186:189], v[56:59]
	v_mfma_f32_16x16x32_bf16 v[44:47], v[154:157], v[194:197], v[44:47]
	v_mfma_f32_16x16x32_bf16 v[40:43], v[162:165], v[194:197], v[40:43]
	v_mfma_f32_16x16x32_bf16 v[28:31], v[154:157], v[202:205], v[28:31]
	v_mfma_f32_16x16x32_bf16 v[24:27], v[162:165], v[202:205], v[24:27]
	v_mfma_f32_16x16x32_bf16 v[12:15], v[154:157], v[210:213], v[12:15]
	v_mfma_f32_16x16x32_bf16 v[8:11], v[162:165], v[210:213], v[8:11]
	s_setprio 0
	s_setprio 1
	v_mfma_f32_16x16x32_bf16 v[52:55], v[166:169], v[182:185], v[52:55]
	v_mfma_f32_16x16x32_bf16 v[48:51], v[174:177], v[182:185], v[48:51]
	v_mfma_f32_16x16x32_bf16 v[36:39], v[166:169], v[190:193], v[36:39]
	v_mfma_f32_16x16x32_bf16 v[32:35], v[174:177], v[190:193], v[32:35]
	v_mfma_f32_16x16x32_bf16 v[20:23], v[166:169], v[198:201], v[20:23]
	v_mfma_f32_16x16x32_bf16 v[16:19], v[174:177], v[198:201], v[16:19]
	v_mfma_f32_16x16x32_bf16 v[4:7], v[166:169], v[206:209], v[4:7]
	v_mfma_f32_16x16x32_bf16 v[0:3], v[174:177], v[206:209], v[0:3]
	v_mfma_f32_16x16x32_bf16 v[52:55], v[170:173], v[186:189], v[52:55]
	v_mfma_f32_16x16x32_bf16 v[48:51], v[178:181], v[186:189], v[48:51]
	v_mfma_f32_16x16x32_bf16 v[36:39], v[170:173], v[194:197], v[36:39]
	v_mfma_f32_16x16x32_bf16 v[32:35], v[178:181], v[194:197], v[32:35]
	v_mfma_f32_16x16x32_bf16 v[20:23], v[170:173], v[202:205], v[20:23]
	v_mfma_f32_16x16x32_bf16 v[16:19], v[178:181], v[202:205], v[16:19]
	v_mfma_f32_16x16x32_bf16 v[4:7], v[170:173], v[210:213], v[4:7]
	v_mfma_f32_16x16x32_bf16 v[0:3], v[178:181], v[210:213], v[0:3]
	s_setprio 0
	s_barrier
	s_add_i32 s37, 0, 0x18000
	s_add_i32 s40, 0, 0x1c000
	v_add_u32_e32 v162, s37, v149
	v_add_u32_e32 v178, s40, v149
	ds_read_b128 v[144:147], v162
	ds_read_b128 v[154:157], v162 offset:1024
	ds_read_b128 v[158:161], v162 offset:2048
	ds_read_b128 v[162:165], v162 offset:3072
	ds_read_b128 v[166:169], v178
	ds_read_b128 v[170:173], v178 offset:1024
	ds_read_b128 v[174:177], v178 offset:2048
	ds_read_b128 v[178:181], v178 offset:3072
	s_add_u32 s38, s54, 0x100000
	s_addc_u32 s39, s55, 0
	s_mov_b32 m0, s57
	v_lshl_add_u64 v[222:223], s[38:39], 0, v[128:129]
	ds_read_b128 v[182:185], v153 offset:32768
	ds_read_b128 v[186:189], v153 offset:33792
	ds_read_b128 v[190:193], v153 offset:34816
	ds_read_b128 v[194:197], v153 offset:35840
	ds_read_b128 v[198:201], v153 offset:36864
	ds_read_b128 v[202:205], v153 offset:37888
	ds_read_b128 v[206:209], v153 offset:38912
	ds_read_b128 v[210:213], v153 offset:39936
	s_mov_b32 m0, s49
	s_nop 0
	global_load_lds_dwordx4 v[218:219], off
	s_mov_b32 m0, s56
	s_nop 0
	global_load_lds_dwordx4 v[220:221], off
	s_mov_b32 m0, s57
	s_nop 0
	global_load_lds_dwordx4 v[222:223], off
	v_lshl_add_u64 v[222:223], s[38:39], 0, v[132:133]
	s_mov_b32 m0, s58
	s_nop 0
	global_load_lds_dwordx4 v[222:223], off
	s_waitcnt vmcnt(8)
	s_waitcnt lgkmcnt(0)
	s_barrier
	s_setprio 1
	s_waitcnt lgkmcnt(0)
	v_mfma_f32_16x16x32_bf16 v[124:127], v[144:147], v[182:185], v[124:127]
	v_mfma_f32_16x16x32_bf16 v[116:119], v[158:161], v[182:185], v[116:119]
	v_mfma_f32_16x16x32_bf16 v[108:111], v[144:147], v[190:193], v[108:111]
	v_mfma_f32_16x16x32_bf16 v[104:107], v[158:161], v[190:193], v[104:107]
	v_mfma_f32_16x16x32_bf16 v[92:95], v[144:147], v[198:201], v[92:95]
	v_mfma_f32_16x16x32_bf16 v[88:91], v[158:161], v[198:201], v[88:91]
	v_mfma_f32_16x16x32_bf16 v[76:79], v[144:147], v[206:209], v[76:79]
	v_mfma_f32_16x16x32_bf16 v[72:75], v[158:161], v[206:209], v[72:75]
	v_mfma_f32_16x16x32_bf16 v[124:127], v[154:157], v[186:189], v[124:127]
	v_mfma_f32_16x16x32_bf16 v[116:119], v[162:165], v[186:189], v[116:119]
	v_mfma_f32_16x16x32_bf16 v[108:111], v[154:157], v[194:197], v[108:111]
	v_mfma_f32_16x16x32_bf16 v[104:107], v[162:165], v[194:197], v[104:107]
	v_mfma_f32_16x16x32_bf16 v[92:95], v[154:157], v[202:205], v[92:95]
	v_mfma_f32_16x16x32_bf16 v[88:91], v[162:165], v[202:205], v[88:91]
	v_mfma_f32_16x16x32_bf16 v[76:79], v[154:157], v[210:213], v[76:79]
	v_mfma_f32_16x16x32_bf16 v[72:75], v[162:165], v[210:213], v[72:75]
	s_setprio 0
	s_setprio 1
	v_mfma_f32_16x16x32_bf16 v[120:123], v[166:169], v[182:185], v[120:123]
	v_mfma_f32_16x16x32_bf16 v[112:115], v[174:177], v[182:185], v[112:115]
	v_mfma_f32_16x16x32_bf16 v[100:103], v[166:169], v[190:193], v[100:103]
	v_mfma_f32_16x16x32_bf16 v[96:99], v[174:177], v[190:193], v[96:99]
	v_mfma_f32_16x16x32_bf16 v[84:87], v[166:169], v[198:201], v[84:87]
	v_mfma_f32_16x16x32_bf16 v[80:83], v[174:177], v[198:201], v[80:83]
	v_mfma_f32_16x16x32_bf16 v[68:71], v[166:169], v[206:209], v[68:71]
	v_mfma_f32_16x16x32_bf16 v[64:67], v[174:177], v[206:209], v[64:67]
	v_mfma_f32_16x16x32_bf16 v[120:123], v[170:173], v[186:189], v[120:123]
	v_mfma_f32_16x16x32_bf16 v[112:115], v[178:181], v[186:189], v[112:115]
	v_mfma_f32_16x16x32_bf16 v[100:103], v[170:173], v[194:197], v[100:103]
	v_mfma_f32_16x16x32_bf16 v[96:99], v[178:181], v[194:197], v[96:99]
	v_mfma_f32_16x16x32_bf16 v[84:87], v[170:173], v[202:205], v[84:87]
	v_mfma_f32_16x16x32_bf16 v[80:83], v[178:181], v[202:205], v[80:83]
	v_mfma_f32_16x16x32_bf16 v[68:71], v[170:173], v[210:213], v[68:71]
	v_mfma_f32_16x16x32_bf16 v[64:67], v[178:181], v[210:213], v[64:67]
	s_setprio 0
	s_barrier
	s_add_i32 s37, s37, s33
	v_lshl_add_u64 v[214:215], v[214:215], 0, s[10:11]
	s_mov_b32 m0, s37
	ds_read_b128 v[182:185], v153 offset:49152
	ds_read_b128 v[186:189], v153 offset:50176
	ds_read_b128 v[190:193], v153 offset:51200
	ds_read_b128 v[194:197], v153 offset:52224
	ds_read_b128 v[198:201], v153 offset:53248
	ds_read_b128 v[202:205], v153 offset:54272
	ds_read_b128 v[206:209], v153 offset:55296
	ds_read_b128 v[210:213], v153 offset:56320
	global_load_lds_dwordx4 v[214:215], off
	s_add_i32 m0, s37, 0x2000
	s_add_u32 s38, s52, 0x100080
	v_lshl_add_u64 v[214:215], v[216:217], 0, s[10:11]
	s_addc_u32 s39, s53, 0
	s_add_i32 s37, s40, s33
	global_load_lds_dwordx4 v[214:215], off
	v_lshl_add_u64 v[214:215], s[38:39], 0, v[130:131]
	s_mov_b32 m0, s37
	s_nop 0
	global_load_lds_dwordx4 v[214:215], off
	v_lshl_add_u64 v[214:215], s[38:39], 0, v[134:135]
	s_add_i32 m0, s37, 0x2000
	s_nop 0
	global_load_lds_dwordx4 v[214:215], off
	v_lshl_add_u64 v[214:215], v[218:219], 0, s[10:11]
	s_mov_b32 m0, s60
	s_nop 0
	global_load_lds_dwordx4 v[214:215], off
	v_lshl_add_u64 v[214:215], v[220:221], 0, s[10:11]
	s_mov_b32 m0, s61
	s_nop 0
	global_load_lds_dwordx4 v[214:215], off
	s_waitcnt vmcnt(8)
	s_waitcnt lgkmcnt(0)
	s_barrier
	s_setprio 1
	s_waitcnt lgkmcnt(0)
	v_mfma_f32_16x16x32_bf16 v[60:63], v[144:147], v[182:185], v[60:63]
	v_mfma_f32_16x16x32_bf16 v[56:59], v[158:161], v[182:185], v[56:59]
	v_mfma_f32_16x16x32_bf16 v[44:47], v[144:147], v[190:193], v[44:47]
	v_mfma_f32_16x16x32_bf16 v[40:43], v[158:161], v[190:193], v[40:43]
	v_mfma_f32_16x16x32_bf16 v[28:31], v[144:147], v[198:201], v[28:31]
	v_mfma_f32_16x16x32_bf16 v[24:27], v[158:161], v[198:201], v[24:27]
	v_mfma_f32_16x16x32_bf16 v[12:15], v[144:147], v[206:209], v[12:15]
	v_mfma_f32_16x16x32_bf16 v[8:11], v[158:161], v[206:209], v[8:11]
	v_mfma_f32_16x16x32_bf16 v[60:63], v[154:157], v[186:189], v[60:63]
	v_mfma_f32_16x16x32_bf16 v[56:59], v[162:165], v[186:189], v[56:59]
	v_mfma_f32_16x16x32_bf16 v[44:47], v[154:157], v[194:197], v[44:47]
	v_mfma_f32_16x16x32_bf16 v[40:43], v[162:165], v[194:197], v[40:43]
	v_mfma_f32_16x16x32_bf16 v[28:31], v[154:157], v[202:205], v[28:31]
	v_mfma_f32_16x16x32_bf16 v[24:27], v[162:165], v[202:205], v[24:27]
	v_mfma_f32_16x16x32_bf16 v[12:15], v[154:157], v[210:213], v[12:15]
	v_mfma_f32_16x16x32_bf16 v[8:11], v[162:165], v[210:213], v[8:11]
	s_setprio 0
	s_setprio 1
	v_mfma_f32_16x16x32_bf16 v[52:55], v[166:169], v[182:185], v[52:55]
	v_mfma_f32_16x16x32_bf16 v[48:51], v[174:177], v[182:185], v[48:51]
	v_mfma_f32_16x16x32_bf16 v[36:39], v[166:169], v[190:193], v[36:39]
	v_mfma_f32_16x16x32_bf16 v[32:35], v[174:177], v[190:193], v[32:35]
	v_mfma_f32_16x16x32_bf16 v[20:23], v[166:169], v[198:201], v[20:23]
	v_mfma_f32_16x16x32_bf16 v[16:19], v[174:177], v[198:201], v[16:19]
	v_mfma_f32_16x16x32_bf16 v[4:7], v[166:169], v[206:209], v[4:7]
	v_mfma_f32_16x16x32_bf16 v[0:3], v[174:177], v[206:209], v[0:3]
	v_mfma_f32_16x16x32_bf16 v[52:55], v[170:173], v[186:189], v[52:55]
	v_mfma_f32_16x16x32_bf16 v[48:51], v[178:181], v[186:189], v[48:51]
	v_mfma_f32_16x16x32_bf16 v[36:39], v[170:173], v[194:197], v[36:39]
	v_mfma_f32_16x16x32_bf16 v[32:35], v[178:181], v[194:197], v[32:35]
	v_mfma_f32_16x16x32_bf16 v[20:23], v[170:173], v[202:205], v[20:23]
	v_mfma_f32_16x16x32_bf16 v[16:19], v[178:181], v[202:205], v[16:19]
	v_mfma_f32_16x16x32_bf16 v[4:7], v[170:173], v[210:213], v[4:7]
	v_mfma_f32_16x16x32_bf16 v[0:3], v[178:181], v[210:213], v[0:3]
	s_setprio 0
	s_barrier
	s_add_i32 s36, s36, 2
	s_add_u32 s50, s50, 0x100
	s_addc_u32 s51, s51, 0
	s_add_u32 s34, s34, 0x100
	s_addc_u32 s35, s35, 0
	s_cmp_gt_u32 s36, 61
	s_cbranch_scc0 .LBB0_679
	s_and_b64 vcc, exec, s[12:13]
	s_cbranch_vccz .LBB0_682
	s_barrier

.LBB0_758:
	ds_read_b128 v[144:147], v153
	ds_read_b128 v[156:159], v153 offset:1024
	ds_read_b128 v[160:163], v153 offset:2048
	ds_read_b128 v[164:167], v153 offset:3072
	ds_read_b128 v[168:171], v154
	ds_read_b128 v[172:175], v154 offset:1024
	ds_read_b128 v[176:179], v154 offset:2048
	ds_read_b128 v[180:183], v154 offset:3072
	s_add_u32 s37, s38, 0xfff00080
	s_addc_u32 s40, s39, -1
	s_cmp_eq_u32 s36, 60
	s_cselect_b32 s49, s13, s40
	s_cselect_b32 s48, s64, s37
	s_cselect_b32 s47, s11, s35
	s_cselect_b32 s46, s65, s34
	v_lshl_add_u64 v[148:149], s[38:39], 0, v[136:137]
	s_add_i32 m0, s76, 0xc000
	ds_read_b128 v[184:187], v155
	ds_read_b128 v[188:191], v155 offset:1024
	ds_read_b128 v[192:195], v155 offset:2048
	ds_read_b128 v[196:199], v155 offset:3072
	ds_read_b128 v[200:203], v155 offset:4096
	ds_read_b128 v[204:207], v155 offset:5120
	ds_read_b128 v[208:211], v155 offset:6144
	ds_read_b128 v[212:215], v155 offset:7168
	global_load_lds_dwordx4 v[148:149], off
	v_lshl_add_u64 v[148:149], s[38:39], 0, v[138:139]
	s_add_i32 m0, s76, 0xe000
	s_nop 0
	global_load_lds_dwordx4 v[148:149], off
	s_waitcnt vmcnt(8)
	s_waitcnt lgkmcnt(0)
	s_barrier
	s_setprio 1
	s_waitcnt lgkmcnt(0)
	v_mfma_f32_16x16x32_bf16 v[124:127], v[144:147], v[184:187], v[124:127]
	v_mfma_f32_16x16x32_bf16 v[120:123], v[160:163], v[184:187], v[120:123]
	v_mfma_f32_16x16x32_bf16 v[108:111], v[144:147], v[192:195], v[108:111]
	v_mfma_f32_16x16x32_bf16 v[104:107], v[160:163], v[192:195], v[104:107]
	v_mfma_f32_16x16x32_bf16 v[92:95], v[144:147], v[200:203], v[92:95]
	v_mfma_f32_16x16x32_bf16 v[88:91], v[160:163], v[200:203], v[88:91]
	v_mfma_f32_16x16x32_bf16 v[76:79], v[144:147], v[208:211], v[76:79]
	v_mfma_f32_16x16x32_bf16 v[72:75], v[160:163], v[208:211], v[72:75]
	v_mfma_f32_16x16x32_bf16 v[124:127], v[156:159], v[188:191], v[124:127]
	v_mfma_f32_16x16x32_bf16 v[120:123], v[164:167], v[188:191], v[120:123]
	v_mfma_f32_16x16x32_bf16 v[108:111], v[156:159], v[196:199], v[108:111]
	v_mfma_f32_16x16x32_bf16 v[104:107], v[164:167], v[196:199], v[104:107]
	v_mfma_f32_16x16x32_bf16 v[92:95], v[156:159], v[204:207], v[92:95]
	v_mfma_f32_16x16x32_bf16 v[88:91], v[164:167], v[204:207], v[88:91]
	v_mfma_f32_16x16x32_bf16 v[76:79], v[156:159], v[212:215], v[76:79]
	v_mfma_f32_16x16x32_bf16 v[72:75], v[164:167], v[212:215], v[72:75]
	s_setprio 0
	s_setprio 1
	v_mfma_f32_16x16x32_bf16 v[116:119], v[168:171], v[184:187], v[116:119]
	v_mfma_f32_16x16x32_bf16 v[112:115], v[176:179], v[184:187], v[112:115]
	v_mfma_f32_16x16x32_bf16 v[100:103], v[168:171], v[192:195], v[100:103]
	v_mfma_f32_16x16x32_bf16 v[96:99], v[176:179], v[192:195], v[96:99]
	v_mfma_f32_16x16x32_bf16 v[84:87], v[168:171], v[200:203], v[84:87]
	v_mfma_f32_16x16x32_bf16 v[80:83], v[176:179], v[200:203], v[80:83]
	v_mfma_f32_16x16x32_bf16 v[68:71], v[168:171], v[208:211], v[68:71]
	v_mfma_f32_16x16x32_bf16 v[64:67], v[176:179], v[208:211], v[64:67]
	v_mfma_f32_16x16x32_bf16 v[116:119], v[172:175], v[188:191], v[116:119]
	v_mfma_f32_16x16x32_bf16 v[112:115], v[180:183], v[188:191], v[112:115]
	v_mfma_f32_16x16x32_bf16 v[100:103], v[172:175], v[196:199], v[100:103]
	v_mfma_f32_16x16x32_bf16 v[96:99], v[180:183], v[196:199], v[96:99]
	v_mfma_f32_16x16x32_bf16 v[84:87], v[172:175], v[204:207], v[84:87]
	v_mfma_f32_16x16x32_bf16 v[80:83], v[180:183], v[204:207], v[80:83]
	v_mfma_f32_16x16x32_bf16 v[68:71], v[172:175], v[212:215], v[68:71]
	v_mfma_f32_16x16x32_bf16 v[64:67], v[180:183], v[212:215], v[64:67]
	s_setprio 0
	s_barrier
	s_add_i32 s37, s61, s67
	v_lshl_add_u64 v[148:149], s[46:47], 0, v[130:131]
	s_mov_b32 m0, s37
	ds_read_b128 v[184:187], v155 offset:16384
	ds_read_b128 v[188:191], v155 offset:17408
	ds_read_b128 v[192:195], v155 offset:18432
	ds_read_b128 v[196:199], v155 offset:19456
	ds_read_b128 v[200:203], v155 offset:20480
	ds_read_b128 v[204:207], v155 offset:21504
	ds_read_b128 v[208:211], v155 offset:22528
	ds_read_b128 v[212:215], v155 offset:23552
	global_load_lds_dwordx4 v[148:149], off
	s_add_i32 m0, s37, 0x2000
	s_add_u32 s40, s46, 0x100000
	v_lshl_add_u64 v[216:217], s[46:47], 0, v[134:135]
	s_addc_u32 s41, s47, 0
	s_add_i32 s37, s62, s67
	global_load_lds_dwordx4 v[216:217], off
	v_lshl_add_u64 v[218:219], s[40:41], 0, v[130:131]
	s_mov_b32 m0, s37
	v_lshl_add_u64 v[220:221], s[48:49], 0, v[132:133]
	global_load_lds_dwordx4 v[218:219], off
	v_lshl_add_u64 v[218:219], s[40:41], 0, v[134:135]
	s_add_i32 m0, s37, 0x2000
	s_nop 0
	global_load_lds_dwordx4 v[218:219], off
	v_lshl_add_u64 v[218:219], s[48:49], 0, v[128:129]
	s_waitcnt vmcnt(6)
	s_waitcnt lgkmcnt(0)
	s_barrier
	s_setprio 1
	s_waitcnt lgkmcnt(0)
	v_mfma_f32_16x16x32_bf16 v[60:63], v[144:147], v[184:187], v[60:63]
	v_mfma_f32_16x16x32_bf16 v[56:59], v[160:163], v[184:187], v[56:59]
	v_mfma_f32_16x16x32_bf16 v[44:47], v[144:147], v[192:195], v[44:47]
	v_mfma_f32_16x16x32_bf16 v[40:43], v[160:163], v[192:195], v[40:43]
	v_mfma_f32_16x16x32_bf16 v[28:31], v[144:147], v[200:203], v[28:31]
	v_mfma_f32_16x16x32_bf16 v[24:27], v[160:163], v[200:203], v[24:27]
	v_mfma_f32_16x16x32_bf16 v[12:15], v[144:147], v[208:211], v[12:15]
	v_mfma_f32_16x16x32_bf16 v[8:11], v[160:163], v[208:211], v[8:11]
	v_mfma_f32_16x16x32_bf16 v[60:63], v[156:159], v[188:191], v[60:63]
	v_mfma_f32_16x16x32_bf16 v[56:59], v[164:167], v[188:191], v[56:59]
	v_mfma_f32_16x16x32_bf16 v[44:47], v[156:159], v[196:199], v[44:47]
	v_mfma_f32_16x16x32_bf16 v[40:43], v[164:167], v[196:199], v[40:43]
	v_mfma_f32_16x16x32_bf16 v[28:31], v[156:159], v[204:207], v[28:31]
	v_mfma_f32_16x16x32_bf16 v[24:27], v[164:167], v[204:207], v[24:27]
	v_mfma_f32_16x16x32_bf16 v[12:15], v[156:159], v[212:215], v[12:15]
	v_mfma_f32_16x16x32_bf16 v[8:11], v[164:167], v[212:215], v[8:11]
	s_setprio 0
	s_setprio 1
	v_mfma_f32_16x16x32_bf16 v[52:55], v[168:171], v[184:187], v[52:55]
	v_mfma_f32_16x16x32_bf16 v[48:51], v[176:179], v[184:187], v[48:51]
	v_mfma_f32_16x16x32_bf16 v[36:39], v[168:171], v[192:195], v[36:39]
	v_mfma_f32_16x16x32_bf16 v[32:35], v[176:179], v[192:195], v[32:35]
	v_mfma_f32_16x16x32_bf16 v[20:23], v[168:171], v[200:203], v[20:23]
	v_mfma_f32_16x16x32_bf16 v[16:19], v[176:179], v[200:203], v[16:19]
	v_mfma_f32_16x16x32_bf16 v[4:7], v[168:171], v[208:211], v[4:7]
	v_mfma_f32_16x16x32_bf16 v[0:3], v[176:179], v[208:211], v[0:3]
	v_mfma_f32_16x16x32_bf16 v[52:55], v[172:175], v[188:191], v[52:55]
	v_mfma_f32_16x16x32_bf16 v[48:51], v[180:183], v[188:191], v[48:51]
	v_mfma_f32_16x16x32_bf16 v[36:39], v[172:175], v[196:199], v[36:39]
	v_mfma_f32_16x16x32_bf16 v[32:35], v[180:183], v[196:199], v[32:35]
	v_mfma_f32_16x16x32_bf16 v[20:23], v[172:175], v[204:207], v[20:23]
	v_mfma_f32_16x16x32_bf16 v[16:19], v[180:183], v[204:207], v[16:19]
	v_mfma_f32_16x16x32_bf16 v[4:7], v[172:175], v[212:215], v[4:7]
	v_mfma_f32_16x16x32_bf16 v[0:3], v[180:183], v[212:215], v[0:3]
	s_setprio 0
	s_barrier
	s_add_i32 s37, 0, 0x18000
	s_add_i32 s42, 0, 0x1c000
	v_add_u32_e32 v164, s37, v151
	v_add_u32_e32 v180, s42, v151
	ds_read_b128 v[144:147], v164
	ds_read_b128 v[156:159], v164 offset:1024
	ds_read_b128 v[160:163], v164 offset:2048
	ds_read_b128 v[164:167], v164 offset:3072
	ds_read_b128 v[168:171], v180
	ds_read_b128 v[172:175], v180 offset:1024
	ds_read_b128 v[176:179], v180 offset:2048
	ds_read_b128 v[180:183], v180 offset:3072
	s_add_u32 s40, s48, 0x100000
	s_addc_u32 s41, s49, 0
	s_mov_b32 m0, s53
	v_lshl_add_u64 v[222:223], s[40:41], 0, v[128:129]
	ds_read_b128 v[184:187], v155 offset:32768
	ds_read_b128 v[188:191], v155 offset:33792
	ds_read_b128 v[192:195], v155 offset:34816
	ds_read_b128 v[196:199], v155 offset:35840
	ds_read_b128 v[200:203], v155 offset:36864
	ds_read_b128 v[204:207], v155 offset:37888
	ds_read_b128 v[208:211], v155 offset:38912
	ds_read_b128 v[212:215], v155 offset:39936
	s_mov_b32 m0, s76
	s_nop 0
	global_load_lds_dwordx4 v[218:219], off
	s_mov_b32 m0, s52
	s_nop 0
	global_load_lds_dwordx4 v[220:221], off
	s_mov_b32 m0, s53
	s_nop 0
	global_load_lds_dwordx4 v[222:223], off
	v_lshl_add_u64 v[222:223], s[40:41], 0, v[132:133]
	s_mov_b32 m0, s54
	s_nop 0
	global_load_lds_dwordx4 v[222:223], off
	s_waitcnt vmcnt(8)
	s_waitcnt lgkmcnt(0)
	s_barrier
	s_setprio 1
	s_waitcnt lgkmcnt(0)
	v_mfma_f32_16x16x32_bf16 v[124:127], v[144:147], v[184:187], v[124:127]
	v_mfma_f32_16x16x32_bf16 v[120:123], v[160:163], v[184:187], v[120:123]
	v_mfma_f32_16x16x32_bf16 v[108:111], v[144:147], v[192:195], v[108:111]
	v_mfma_f32_16x16x32_bf16 v[104:107], v[160:163], v[192:195], v[104:107]
	v_mfma_f32_16x16x32_bf16 v[92:95], v[144:147], v[200:203], v[92:95]
	v_mfma_f32_16x16x32_bf16 v[88:91], v[160:163], v[200:203], v[88:91]
	v_mfma_f32_16x16x32_bf16 v[76:79], v[144:147], v[208:211], v[76:79]
	v_mfma_f32_16x16x32_bf16 v[72:75], v[160:163], v[208:211], v[72:75]
	v_mfma_f32_16x16x32_bf16 v[124:127], v[156:159], v[188:191], v[124:127]
	v_mfma_f32_16x16x32_bf16 v[120:123], v[164:167], v[188:191], v[120:123]
	v_mfma_f32_16x16x32_bf16 v[108:111], v[156:159], v[196:199], v[108:111]
	v_mfma_f32_16x16x32_bf16 v[104:107], v[164:167], v[196:199], v[104:107]
	v_mfma_f32_16x16x32_bf16 v[92:95], v[156:159], v[204:207], v[92:95]
	v_mfma_f32_16x16x32_bf16 v[88:91], v[164:167], v[204:207], v[88:91]
	v_mfma_f32_16x16x32_bf16 v[76:79], v[156:159], v[212:215], v[76:79]
	v_mfma_f32_16x16x32_bf16 v[72:75], v[164:167], v[212:215], v[72:75]
	s_setprio 0
	s_setprio 1
	v_mfma_f32_16x16x32_bf16 v[116:119], v[168:171], v[184:187], v[116:119]
	v_mfma_f32_16x16x32_bf16 v[112:115], v[176:179], v[184:187], v[112:115]
	v_mfma_f32_16x16x32_bf16 v[100:103], v[168:171], v[192:195], v[100:103]
	v_mfma_f32_16x16x32_bf16 v[96:99], v[176:179], v[192:195], v[96:99]
	v_mfma_f32_16x16x32_bf16 v[84:87], v[168:171], v[200:203], v[84:87]
	v_mfma_f32_16x16x32_bf16 v[80:83], v[176:179], v[200:203], v[80:83]
	v_mfma_f32_16x16x32_bf16 v[68:71], v[168:171], v[208:211], v[68:71]
	v_mfma_f32_16x16x32_bf16 v[64:67], v[176:179], v[208:211], v[64:67]
	v_mfma_f32_16x16x32_bf16 v[116:119], v[172:175], v[188:191], v[116:119]
	v_mfma_f32_16x16x32_bf16 v[112:115], v[180:183], v[188:191], v[112:115]
	v_mfma_f32_16x16x32_bf16 v[100:103], v[172:175], v[196:199], v[100:103]
	v_mfma_f32_16x16x32_bf16 v[96:99], v[180:183], v[196:199], v[96:99]
	v_mfma_f32_16x16x32_bf16 v[84:87], v[172:175], v[204:207], v[84:87]
	v_mfma_f32_16x16x32_bf16 v[80:83], v[180:183], v[204:207], v[80:83]
	v_mfma_f32_16x16x32_bf16 v[68:71], v[172:175], v[212:215], v[68:71]
	v_mfma_f32_16x16x32_bf16 v[64:67], v[180:183], v[212:215], v[64:67]
	s_setprio 0
	s_barrier
	s_add_i32 s37, s37, s67
	v_lshl_add_u64 v[148:149], v[148:149], 0, s[6:7]
	s_mov_b32 m0, s37
	ds_read_b128 v[184:187], v155 offset:49152
	ds_read_b128 v[188:191], v155 offset:50176
	ds_read_b128 v[192:195], v155 offset:51200
	ds_read_b128 v[196:199], v155 offset:52224
	ds_read_b128 v[200:203], v155 offset:53248
	ds_read_b128 v[204:207], v155 offset:54272
	ds_read_b128 v[208:211], v155 offset:55296
	ds_read_b128 v[212:215], v155 offset:56320
	global_load_lds_dwordx4 v[148:149], off
	s_add_i32 m0, s37, 0x2000
	s_add_u32 s40, s46, 0x100080
	v_lshl_add_u64 v[148:149], v[216:217], 0, s[6:7]
	s_addc_u32 s41, s47, 0
	s_add_i32 s37, s42, s67
	global_load_lds_dwordx4 v[148:149], off
	v_lshl_add_u64 v[148:149], s[40:41], 0, v[130:131]
	s_mov_b32 m0, s37
	s_nop 0
	global_load_lds_dwordx4 v[148:149], off
	v_lshl_add_u64 v[148:149], s[40:41], 0, v[134:135]
	s_add_i32 m0, s37, 0x2000
	s_nop 0
	global_load_lds_dwordx4 v[148:149], off
	v_lshl_add_u64 v[148:149], v[218:219], 0, s[6:7]
	s_mov_b32 m0, s56
	s_nop 0
	global_load_lds_dwordx4 v[148:149], off
	v_lshl_add_u64 v[148:149], v[220:221], 0, s[6:7]
	s_mov_b32 m0, s57
	s_nop 0
	global_load_lds_dwordx4 v[148:149], off
	s_waitcnt vmcnt(8)
	s_waitcnt lgkmcnt(0)
	s_barrier
	s_setprio 1
	s_waitcnt lgkmcnt(0)
	v_mfma_f32_16x16x32_bf16 v[60:63], v[144:147], v[184:187], v[60:63]
	v_mfma_f32_16x16x32_bf16 v[56:59], v[160:163], v[184:187], v[56:59]
	v_mfma_f32_16x16x32_bf16 v[44:47], v[144:147], v[192:195], v[44:47]
	v_mfma_f32_16x16x32_bf16 v[40:43], v[160:163], v[192:195], v[40:43]
	v_mfma_f32_16x16x32_bf16 v[28:31], v[144:147], v[200:203], v[28:31]
	v_mfma_f32_16x16x32_bf16 v[24:27], v[160:163], v[200:203], v[24:27]
	v_mfma_f32_16x16x32_bf16 v[12:15], v[144:147], v[208:211], v[12:15]
	v_mfma_f32_16x16x32_bf16 v[8:11], v[160:163], v[208:211], v[8:11]
	v_mfma_f32_16x16x32_bf16 v[60:63], v[156:159], v[188:191], v[60:63]
	v_mfma_f32_16x16x32_bf16 v[56:59], v[164:167], v[188:191], v[56:59]
	v_mfma_f32_16x16x32_bf16 v[44:47], v[156:159], v[196:199], v[44:47]
	v_mfma_f32_16x16x32_bf16 v[40:43], v[164:167], v[196:199], v[40:43]
	v_mfma_f32_16x16x32_bf16 v[28:31], v[156:159], v[204:207], v[28:31]
	v_mfma_f32_16x16x32_bf16 v[24:27], v[164:167], v[204:207], v[24:27]
	v_mfma_f32_16x16x32_bf16 v[12:15], v[156:159], v[212:215], v[12:15]
	v_mfma_f32_16x16x32_bf16 v[8:11], v[164:167], v[212:215], v[8:11]
	s_setprio 0
	s_setprio 1
	v_mfma_f32_16x16x32_bf16 v[52:55], v[168:171], v[184:187], v[52:55]
	v_mfma_f32_16x16x32_bf16 v[48:51], v[176:179], v[184:187], v[48:51]
	v_mfma_f32_16x16x32_bf16 v[36:39], v[168:171], v[192:195], v[36:39]
	v_mfma_f32_16x16x32_bf16 v[32:35], v[176:179], v[192:195], v[32:35]
	v_mfma_f32_16x16x32_bf16 v[20:23], v[168:171], v[200:203], v[20:23]
	v_mfma_f32_16x16x32_bf16 v[16:19], v[176:179], v[200:203], v[16:19]
	v_mfma_f32_16x16x32_bf16 v[4:7], v[168:171], v[208:211], v[4:7]
	v_mfma_f32_16x16x32_bf16 v[0:3], v[176:179], v[208:211], v[0:3]
	v_mfma_f32_16x16x32_bf16 v[52:55], v[172:175], v[188:191], v[52:55]
	v_mfma_f32_16x16x32_bf16 v[48:51], v[180:183], v[188:191], v[48:51]
	v_mfma_f32_16x16x32_bf16 v[36:39], v[172:175], v[196:199], v[36:39]
	v_mfma_f32_16x16x32_bf16 v[32:35], v[180:183], v[196:199], v[32:35]
	v_mfma_f32_16x16x32_bf16 v[20:23], v[172:175], v[204:207], v[20:23]
	v_mfma_f32_16x16x32_bf16 v[16:19], v[180:183], v[204:207], v[16:19]
	v_mfma_f32_16x16x32_bf16 v[4:7], v[172:175], v[212:215], v[4:7]
	v_mfma_f32_16x16x32_bf16 v[0:3], v[180:183], v[212:215], v[0:3]
	s_setprio 0
	s_barrier
	s_add_i32 s36, s36, 2
	s_add_u32 s38, s38, 0x100
	s_addc_u32 s39, s39, 0
	s_add_u32 s34, s34, 0x100
	s_addc_u32 s35, s35, 0
	s_cmp_gt_u32 s36, 61
	s_cbranch_scc0 .LBB0_758
	s_and_b64 vcc, exec, s[8:9]
	s_cbranch_vccz .LBB0_761
	s_barrier

.LBB0_914:
	ds_read_b128 v[128:131], v187
	ds_read_b128 v[132:135], v187 offset:1024
	ds_read_b128 v[136:139], v187 offset:2048
	ds_read_b128 v[140:143], v187 offset:3072
	ds_read_b128 v[144:147], v188
	ds_read_b128 v[148:151], v188 offset:1024
	ds_read_b128 v[152:155], v188 offset:2048
	ds_read_b128 v[156:159], v188 offset:3072
	s_add_u32 s52, s50, 0x100
	s_addc_u32 s53, s51, 0
	s_cmp_eq_u32 s96, 60
	s_cselect_b32 s57, s41, s53
	s_cselect_b32 s56, s47, s52
	s_cselect_b32 s55, s39, s49
	s_cselect_b32 s54, s34, s35
	v_lshl_add_u64 v[160:161], s[50:51], 0, v[170:171]
	s_add_i32 m0, s67, 0xc000
	ds_read_b128 v[178:181], v189
	ds_read_b128 v[192:195], v189 offset:1024
	ds_read_b128 v[196:199], v189 offset:2048
	ds_read_b128 v[200:203], v189 offset:3072
	ds_read_b128 v[204:207], v189 offset:4096
	ds_read_b128 v[208:211], v189 offset:5120
	ds_read_b128 v[212:215], v189 offset:6144
	ds_read_b128 v[216:219], v189 offset:7168
	global_load_lds_dwordx4 v[160:161], off
	v_lshl_add_u64 v[160:161], s[50:51], 0, v[172:173]
	s_add_i32 m0, s67, 0xe000
	s_nop 0
	global_load_lds_dwordx4 v[160:161], off
	s_waitcnt vmcnt(8)
	s_waitcnt lgkmcnt(0)
	s_barrier
	s_setprio 1
	s_waitcnt lgkmcnt(0)
	v_mfma_f32_16x16x32_bf16 v[124:127], v[128:131], v[178:181], v[124:127]
	v_mfma_f32_16x16x32_bf16 v[60:63], v[136:139], v[178:181], v[60:63]
	v_mfma_f32_16x16x32_bf16 v[116:119], v[128:131], v[196:199], v[116:119]
	v_mfma_f32_16x16x32_bf16 v[56:59], v[136:139], v[196:199], v[56:59]
	v_mfma_f32_16x16x32_bf16 v[108:111], v[128:131], v[204:207], v[108:111]
	v_mfma_f32_16x16x32_bf16 v[44:47], v[136:139], v[204:207], v[44:47]
	v_mfma_f32_16x16x32_bf16 v[104:107], v[128:131], v[212:215], v[104:107]
	v_mfma_f32_16x16x32_bf16 v[40:43], v[136:139], v[212:215], v[40:43]
	v_mfma_f32_16x16x32_bf16 v[124:127], v[132:135], v[192:195], v[124:127]
	v_mfma_f32_16x16x32_bf16 v[60:63], v[140:143], v[192:195], v[60:63]
	v_mfma_f32_16x16x32_bf16 v[116:119], v[132:135], v[200:203], v[116:119]
	v_mfma_f32_16x16x32_bf16 v[56:59], v[140:143], v[200:203], v[56:59]
	v_mfma_f32_16x16x32_bf16 v[108:111], v[132:135], v[208:211], v[108:111]
	v_mfma_f32_16x16x32_bf16 v[44:47], v[140:143], v[208:211], v[44:47]
	v_mfma_f32_16x16x32_bf16 v[104:107], v[132:135], v[216:219], v[104:107]
	v_mfma_f32_16x16x32_bf16 v[40:43], v[140:143], v[216:219], v[40:43]
	s_setprio 0
	s_setprio 1
	v_mfma_f32_16x16x32_bf16 v[120:123], v[144:147], v[178:181], v[120:123]
	v_mfma_f32_16x16x32_bf16 v[52:55], v[152:155], v[178:181], v[52:55]
	v_mfma_f32_16x16x32_bf16 v[112:115], v[144:147], v[196:199], v[112:115]
	v_mfma_f32_16x16x32_bf16 v[48:51], v[152:155], v[196:199], v[48:51]
	v_mfma_f32_16x16x32_bf16 v[100:103], v[144:147], v[204:207], v[100:103]
	v_mfma_f32_16x16x32_bf16 v[36:39], v[152:155], v[204:207], v[36:39]
	v_mfma_f32_16x16x32_bf16 v[96:99], v[144:147], v[212:215], v[96:99]
	v_mfma_f32_16x16x32_bf16 v[32:35], v[152:155], v[212:215], v[32:35]
	v_mfma_f32_16x16x32_bf16 v[120:123], v[148:151], v[192:195], v[120:123]
	v_mfma_f32_16x16x32_bf16 v[52:55], v[156:159], v[192:195], v[52:55]
	v_mfma_f32_16x16x32_bf16 v[112:115], v[148:151], v[200:203], v[112:115]
	v_mfma_f32_16x16x32_bf16 v[48:51], v[156:159], v[200:203], v[48:51]
	v_mfma_f32_16x16x32_bf16 v[100:103], v[148:151], v[208:211], v[100:103]
	v_mfma_f32_16x16x32_bf16 v[36:39], v[156:159], v[208:211], v[36:39]
	v_mfma_f32_16x16x32_bf16 v[96:99], v[148:151], v[216:219], v[96:99]
	v_mfma_f32_16x16x32_bf16 v[32:35], v[156:159], v[216:219], v[32:35]
	s_setprio 0
	s_barrier
	s_add_i32 s50, s92, s66
	v_lshl_add_u64 v[160:161], s[54:55], 0, v[164:165]
	s_mov_b32 m0, s50
	ds_read_b128 v[178:181], v189 offset:16384
	ds_read_b128 v[192:195], v189 offset:17408
	ds_read_b128 v[196:199], v189 offset:18432
	ds_read_b128 v[200:203], v189 offset:19456
	ds_read_b128 v[204:207], v189 offset:20480
	ds_read_b128 v[208:211], v189 offset:21504
	ds_read_b128 v[212:215], v189 offset:22528
	ds_read_b128 v[216:219], v189 offset:23552
	global_load_lds_dwordx4 v[160:161], off
	s_add_i32 m0, s50, 0x2000
	s_add_u32 s50, s54, 0x100000
	v_lshl_add_u64 v[182:183], s[54:55], 0, v[168:169]
	s_addc_u32 s51, s55, 0
	s_add_i32 s97, s93, s66
	global_load_lds_dwordx4 v[182:183], off
	v_lshl_add_u64 v[220:221], s[50:51], 0, v[164:165]
	s_mov_b32 m0, s97
	v_lshl_add_u64 v[222:223], s[56:57], 0, v[166:167]
	global_load_lds_dwordx4 v[220:221], off
	v_lshl_add_u64 v[220:221], s[50:51], 0, v[168:169]
	s_add_i32 m0, s97, 0x2000
	s_nop 0
	global_load_lds_dwordx4 v[220:221], off
	v_lshl_add_u64 v[220:221], s[56:57], 0, v[162:163]
	s_waitcnt vmcnt(6)
	s_waitcnt lgkmcnt(0)
	s_barrier
	s_setprio 1
	s_waitcnt lgkmcnt(0)
	v_mfma_f32_16x16x32_bf16 v[92:95], v[128:131], v[178:181], v[92:95]
	v_mfma_f32_16x16x32_bf16 v[28:31], v[136:139], v[178:181], v[28:31]
	v_mfma_f32_16x16x32_bf16 v[84:87], v[128:131], v[196:199], v[84:87]
	v_mfma_f32_16x16x32_bf16 v[24:27], v[136:139], v[196:199], v[24:27]
	v_mfma_f32_16x16x32_bf16 v[76:79], v[128:131], v[204:207], v[76:79]
	v_mfma_f32_16x16x32_bf16 v[12:15], v[136:139], v[204:207], v[12:15]
	v_mfma_f32_16x16x32_bf16 v[72:75], v[128:131], v[212:215], v[72:75]
	v_mfma_f32_16x16x32_bf16 v[8:11], v[136:139], v[212:215], v[8:11]
	v_mfma_f32_16x16x32_bf16 v[92:95], v[132:135], v[192:195], v[92:95]
	v_mfma_f32_16x16x32_bf16 v[28:31], v[140:143], v[192:195], v[28:31]
	v_mfma_f32_16x16x32_bf16 v[84:87], v[132:135], v[200:203], v[84:87]
	v_mfma_f32_16x16x32_bf16 v[24:27], v[140:143], v[200:203], v[24:27]
	v_mfma_f32_16x16x32_bf16 v[76:79], v[132:135], v[208:211], v[76:79]
	v_mfma_f32_16x16x32_bf16 v[12:15], v[140:143], v[208:211], v[12:15]
	v_mfma_f32_16x16x32_bf16 v[72:75], v[132:135], v[216:219], v[72:75]
	v_mfma_f32_16x16x32_bf16 v[8:11], v[140:143], v[216:219], v[8:11]
	s_setprio 0
	s_setprio 1
	v_mfma_f32_16x16x32_bf16 v[88:91], v[144:147], v[178:181], v[88:91]
	v_mfma_f32_16x16x32_bf16 v[20:23], v[152:155], v[178:181], v[20:23]
	v_mfma_f32_16x16x32_bf16 v[80:83], v[144:147], v[196:199], v[80:83]
	v_mfma_f32_16x16x32_bf16 v[16:19], v[152:155], v[196:199], v[16:19]
	v_mfma_f32_16x16x32_bf16 v[68:71], v[144:147], v[204:207], v[68:71]
	v_mfma_f32_16x16x32_bf16 v[4:7], v[152:155], v[204:207], v[4:7]
	v_mfma_f32_16x16x32_bf16 v[64:67], v[144:147], v[212:215], v[64:67]
	v_mfma_f32_16x16x32_bf16 v[0:3], v[152:155], v[212:215], v[0:3]
	v_mfma_f32_16x16x32_bf16 v[88:91], v[148:151], v[192:195], v[88:91]
	v_mfma_f32_16x16x32_bf16 v[20:23], v[156:159], v[192:195], v[20:23]
	v_mfma_f32_16x16x32_bf16 v[80:83], v[148:151], v[200:203], v[80:83]
	v_mfma_f32_16x16x32_bf16 v[16:19], v[156:159], v[200:203], v[16:19]
	v_mfma_f32_16x16x32_bf16 v[68:71], v[148:151], v[208:211], v[68:71]
	v_mfma_f32_16x16x32_bf16 v[4:7], v[156:159], v[208:211], v[4:7]
	v_mfma_f32_16x16x32_bf16 v[64:67], v[148:151], v[216:219], v[64:67]
	v_mfma_f32_16x16x32_bf16 v[0:3], v[156:159], v[216:219], v[0:3]
	s_setprio 0
	s_barrier
	s_add_i32 s97, 0, 0x18000
	s_add_i32 vcc_lo, 0, 0x1c000
	v_add_u32_e32 v140, s97, v184
	v_add_u32_e32 v156, vcc_lo, v184
	ds_read_b128 v[128:131], v140
	ds_read_b128 v[132:135], v140 offset:1024
	ds_read_b128 v[136:139], v140 offset:2048
	ds_read_b128 v[140:143], v140 offset:3072
	ds_read_b128 v[144:147], v156
	ds_read_b128 v[148:151], v156 offset:1024
	ds_read_b128 v[152:155], v156 offset:2048
	ds_read_b128 v[156:159], v156 offset:3072
	s_add_u32 s50, s56, 0x100000
	s_addc_u32 s51, s57, 0
	s_mov_b32 m0, s69
	v_lshl_add_u64 v[226:227], s[50:51], 0, v[162:163]
	ds_read_b128 v[178:181], v189 offset:32768
	ds_read_b128 v[192:195], v189 offset:33792
	ds_read_b128 v[196:199], v189 offset:34816
	ds_read_b128 v[200:203], v189 offset:35840
	ds_read_b128 v[204:207], v189 offset:36864
	ds_read_b128 v[208:211], v189 offset:37888
	ds_read_b128 v[212:215], v189 offset:38912
	ds_read_b128 v[216:219], v189 offset:39936
	s_mov_b32 m0, s67
	s_nop 0
	global_load_lds_dwordx4 v[220:221], off
	s_mov_b32 m0, s68
	s_nop 0
	global_load_lds_dwordx4 v[222:223], off
	s_mov_b32 m0, s69
	s_nop 0
	global_load_lds_dwordx4 v[226:227], off
	v_lshl_add_u64 v[226:227], s[50:51], 0, v[166:167]
	s_mov_b32 m0, s76
	s_nop 0
	global_load_lds_dwordx4 v[226:227], off
	s_waitcnt vmcnt(8)
	s_waitcnt lgkmcnt(0)
	s_barrier
	s_setprio 1
	s_waitcnt lgkmcnt(0)
	v_mfma_f32_16x16x32_bf16 v[124:127], v[128:131], v[178:181], v[124:127]
	v_mfma_f32_16x16x32_bf16 v[60:63], v[136:139], v[178:181], v[60:63]
	v_mfma_f32_16x16x32_bf16 v[116:119], v[128:131], v[196:199], v[116:119]
	v_mfma_f32_16x16x32_bf16 v[56:59], v[136:139], v[196:199], v[56:59]
	v_mfma_f32_16x16x32_bf16 v[108:111], v[128:131], v[204:207], v[108:111]
	v_mfma_f32_16x16x32_bf16 v[44:47], v[136:139], v[204:207], v[44:47]
	v_mfma_f32_16x16x32_bf16 v[104:107], v[128:131], v[212:215], v[104:107]
	v_mfma_f32_16x16x32_bf16 v[40:43], v[136:139], v[212:215], v[40:43]
	v_mfma_f32_16x16x32_bf16 v[124:127], v[132:135], v[192:195], v[124:127]
	v_mfma_f32_16x16x32_bf16 v[60:63], v[140:143], v[192:195], v[60:63]
	v_mfma_f32_16x16x32_bf16 v[116:119], v[132:135], v[200:203], v[116:119]
	v_mfma_f32_16x16x32_bf16 v[56:59], v[140:143], v[200:203], v[56:59]
	v_mfma_f32_16x16x32_bf16 v[108:111], v[132:135], v[208:211], v[108:111]
	v_mfma_f32_16x16x32_bf16 v[44:47], v[140:143], v[208:211], v[44:47]
	v_mfma_f32_16x16x32_bf16 v[104:107], v[132:135], v[216:219], v[104:107]
	v_mfma_f32_16x16x32_bf16 v[40:43], v[140:143], v[216:219], v[40:43]
	s_setprio 0
	s_setprio 1
	v_mfma_f32_16x16x32_bf16 v[120:123], v[144:147], v[178:181], v[120:123]
	v_mfma_f32_16x16x32_bf16 v[52:55], v[152:155], v[178:181], v[52:55]
	v_mfma_f32_16x16x32_bf16 v[112:115], v[144:147], v[196:199], v[112:115]
	v_mfma_f32_16x16x32_bf16 v[48:51], v[152:155], v[196:199], v[48:51]
	v_mfma_f32_16x16x32_bf16 v[100:103], v[144:147], v[204:207], v[100:103]
	v_mfma_f32_16x16x32_bf16 v[36:39], v[152:155], v[204:207], v[36:39]
	v_mfma_f32_16x16x32_bf16 v[96:99], v[144:147], v[212:215], v[96:99]
	v_mfma_f32_16x16x32_bf16 v[32:35], v[152:155], v[212:215], v[32:35]
	v_mfma_f32_16x16x32_bf16 v[120:123], v[148:151], v[192:195], v[120:123]
	v_mfma_f32_16x16x32_bf16 v[52:55], v[156:159], v[192:195], v[52:55]
	v_mfma_f32_16x16x32_bf16 v[112:115], v[148:151], v[200:203], v[112:115]
	v_mfma_f32_16x16x32_bf16 v[48:51], v[156:159], v[200:203], v[48:51]
	v_mfma_f32_16x16x32_bf16 v[100:103], v[148:151], v[208:211], v[100:103]
	v_mfma_f32_16x16x32_bf16 v[36:39], v[156:159], v[208:211], v[36:39]
	v_mfma_f32_16x16x32_bf16 v[96:99], v[148:151], v[216:219], v[96:99]
	v_mfma_f32_16x16x32_bf16 v[32:35], v[156:159], v[216:219], v[32:35]
	s_setprio 0
	s_barrier
	s_add_i32 s50, s97, s66
	v_lshl_add_u64 v[160:161], v[160:161], 0, s[10:11]
	s_mov_b32 m0, s50
	ds_read_b128 v[178:181], v189 offset:49152
	ds_read_b128 v[192:195], v189 offset:50176
	ds_read_b128 v[196:199], v189 offset:51200
	ds_read_b128 v[200:203], v189 offset:52224
	ds_read_b128 v[204:207], v189 offset:53248
	ds_read_b128 v[208:211], v189 offset:54272
	ds_read_b128 v[212:215], v189 offset:55296
	ds_read_b128 v[216:219], v189 offset:56320
	global_load_lds_dwordx4 v[160:161], off
	s_add_i32 m0, s50, 0x2000
	s_add_u32 s50, s54, 0x100080
	v_lshl_add_u64 v[160:161], v[182:183], 0, s[10:11]
	s_addc_u32 s51, s55, 0
	s_add_i32 s54, vcc_lo, s66
	global_load_lds_dwordx4 v[160:161], off
	v_lshl_add_u64 v[160:161], s[50:51], 0, v[164:165]
	s_mov_b32 m0, s54
	s_nop 0
	global_load_lds_dwordx4 v[160:161], off
	v_lshl_add_u64 v[160:161], s[50:51], 0, v[168:169]
	s_add_i32 m0, s54, 0x2000
	s_nop 0
	global_load_lds_dwordx4 v[160:161], off
	v_lshl_add_u64 v[160:161], v[220:221], 0, s[10:11]
	s_mov_b32 m0, s84
	s_nop 0
	global_load_lds_dwordx4 v[160:161], off
	v_lshl_add_u64 v[160:161], v[222:223], 0, s[10:11]
	s_mov_b32 m0, s85
	s_nop 0
	global_load_lds_dwordx4 v[160:161], off
	s_waitcnt vmcnt(8)
	s_waitcnt lgkmcnt(0)
	s_barrier
	s_setprio 1
	s_waitcnt lgkmcnt(0)
	v_mfma_f32_16x16x32_bf16 v[92:95], v[128:131], v[178:181], v[92:95]
	v_mfma_f32_16x16x32_bf16 v[28:31], v[136:139], v[178:181], v[28:31]
	v_mfma_f32_16x16x32_bf16 v[84:87], v[128:131], v[196:199], v[84:87]
	v_mfma_f32_16x16x32_bf16 v[24:27], v[136:139], v[196:199], v[24:27]
	v_mfma_f32_16x16x32_bf16 v[76:79], v[128:131], v[204:207], v[76:79]
	v_mfma_f32_16x16x32_bf16 v[12:15], v[136:139], v[204:207], v[12:15]
	v_mfma_f32_16x16x32_bf16 v[72:75], v[128:131], v[212:215], v[72:75]
	v_mfma_f32_16x16x32_bf16 v[8:11], v[136:139], v[212:215], v[8:11]
	v_mfma_f32_16x16x32_bf16 v[92:95], v[132:135], v[192:195], v[92:95]
	v_mfma_f32_16x16x32_bf16 v[28:31], v[140:143], v[192:195], v[28:31]
	v_mfma_f32_16x16x32_bf16 v[84:87], v[132:135], v[200:203], v[84:87]
	v_mfma_f32_16x16x32_bf16 v[24:27], v[140:143], v[200:203], v[24:27]
	v_mfma_f32_16x16x32_bf16 v[76:79], v[132:135], v[208:211], v[76:79]
	v_mfma_f32_16x16x32_bf16 v[12:15], v[140:143], v[208:211], v[12:15]
	v_mfma_f32_16x16x32_bf16 v[72:75], v[132:135], v[216:219], v[72:75]
	v_mfma_f32_16x16x32_bf16 v[8:11], v[140:143], v[216:219], v[8:11]
	s_setprio 0
	s_setprio 1
	v_mfma_f32_16x16x32_bf16 v[88:91], v[144:147], v[178:181], v[88:91]
	v_mfma_f32_16x16x32_bf16 v[20:23], v[152:155], v[178:181], v[20:23]
	v_mfma_f32_16x16x32_bf16 v[80:83], v[144:147], v[196:199], v[80:83]
	v_mfma_f32_16x16x32_bf16 v[16:19], v[152:155], v[196:199], v[16:19]
	v_mfma_f32_16x16x32_bf16 v[68:71], v[144:147], v[204:207], v[68:71]
	v_mfma_f32_16x16x32_bf16 v[4:7], v[152:155], v[204:207], v[4:7]
	v_mfma_f32_16x16x32_bf16 v[64:67], v[144:147], v[212:215], v[64:67]
	v_mfma_f32_16x16x32_bf16 v[0:3], v[152:155], v[212:215], v[0:3]
	v_mfma_f32_16x16x32_bf16 v[88:91], v[148:151], v[192:195], v[88:91]
	v_mfma_f32_16x16x32_bf16 v[20:23], v[156:159], v[192:195], v[20:23]
	v_mfma_f32_16x16x32_bf16 v[80:83], v[148:151], v[200:203], v[80:83]
	v_mfma_f32_16x16x32_bf16 v[16:19], v[156:159], v[200:203], v[16:19]
	v_mfma_f32_16x16x32_bf16 v[68:71], v[148:151], v[208:211], v[68:71]
	v_mfma_f32_16x16x32_bf16 v[4:7], v[156:159], v[208:211], v[4:7]
	v_mfma_f32_16x16x32_bf16 v[64:67], v[148:151], v[216:219], v[64:67]
	v_mfma_f32_16x16x32_bf16 v[0:3], v[156:159], v[216:219], v[0:3]
	s_setprio 0
	s_barrier
	s_add_i32 s96, s96, 2
	s_add_u32 s35, s35, 0x100
	s_addc_u32 s49, s49, 0
	s_cmp_gt_u32 s96, 61
	s_mov_b64 s[50:51], s[52:53]
	s_cbranch_scc0 .LBB0_914
	s_lshl_b32 s34, s46, 2
	v_lshl_or_b32 v178, s48, 7, v186
	s_add_i32 s34, s34, s65
	v_ashrrev_i32_e32 v179, 31, v178
	s_mul_hi_i32 s35, s34, 0x30000
	s_mul_i32 s39, s34, 0x30000
	s_and_saveexec_b64 s[48:49], s[0:1]
	s_cbranch_execz .LBB0_917
	s_add_u32 s50, s79, s39
	s_addc_u32 s51, s81, s35
	v_lshl_add_u64 v[132:133], v[178:179], 1, s[50:51]
	v_add_co_u32_e32 v134, vcc, s78, v132
	s_nop 2
	v_cvt_pk_bf16_f32 v128, v124, v125
	s_nop 2
	v_cvt_pk_bf16_f32 v129, v126, v127
	s_nop 2
	v_cvt_pk_bf16_f32 v130, v60, v61
	s_nop 2
	v_cvt_pk_bf16_f32 v131, v62, v63
	s_nop 1
	v_addc_co_u32_e32 v135, vcc, 0, v133, vcc
	s_mov_b32 s17, 0xc000
	global_store_dwordx4 v[132:133], v[128:131], off
	s_nop 1
	s_nop 2
	v_cvt_pk_bf16_f32 v128, v120, v121
	s_nop 2
	v_cvt_pk_bf16_f32 v129, v122, v123
	s_nop 2
	v_cvt_pk_bf16_f32 v130, v52, v53
	s_nop 2
	v_cvt_pk_bf16_f32 v131, v54, v55
	global_store_dwordx4 v[134:135], v[128:131], off
	v_add_co_u32_e32 v134, vcc, s17, v132
	s_nop 0
	s_nop 2
	v_cvt_pk_bf16_f32 v128, v116, v117
	s_nop 2
	v_cvt_pk_bf16_f32 v129, v118, v119
	s_nop 2
	v_cvt_pk_bf16_f32 v130, v56, v57
	s_nop 2
	v_cvt_pk_bf16_f32 v131, v58, v59
	s_nop 0
	v_addc_co_u32_e32 v135, vcc, 0, v133, vcc
	v_add_co_u32_e32 v132, vcc, 0x12000, v132
	global_store_dwordx4 v[134:135], v[128:131], off
	s_nop 0
	v_addc_co_u32_e32 v133, vcc, 0, v133, vcc
	s_nop 2
	v_cvt_pk_bf16_f32 v128, v112, v113
	s_nop 2
	v_cvt_pk_bf16_f32 v129, v114, v115
	s_nop 2
	v_cvt_pk_bf16_f32 v130, v48, v49
	s_nop 2
	v_cvt_pk_bf16_f32 v131, v50, v51
	global_store_dwordx4 v[132:133], v[128:131], off

.LBB0_1077:
	ds_read_b128 v[144:147], v153
	ds_read_b128 v[156:159], v153 offset:1024
	ds_read_b128 v[160:163], v153 offset:2048
	ds_read_b128 v[164:167], v153 offset:3072
	ds_read_b128 v[168:171], v154
	ds_read_b128 v[172:175], v154 offset:1024
	ds_read_b128 v[176:179], v154 offset:2048
	ds_read_b128 v[180:183], v154 offset:3072
	s_add_u32 s28, s26, 0x100
	s_addc_u32 s29, s27, 0
	s_cmpk_eq_i32 s53, 0xbc
	s_cselect_b32 s37, s3, s29
	s_cselect_b32 s36, s2, s28
	s_cselect_b32 s31, s25, s35
	s_cselect_b32 s30, s24, s34
	v_lshl_add_u64 v[148:149], s[26:27], 0, v[136:137]
	s_add_i32 m0, s39, 0xc000
	ds_read_b128 v[184:187], v155
	ds_read_b128 v[188:191], v155 offset:1024
	ds_read_b128 v[192:195], v155 offset:2048
	ds_read_b128 v[196:199], v155 offset:3072
	ds_read_b128 v[200:203], v155 offset:4096
	ds_read_b128 v[204:207], v155 offset:5120
	ds_read_b128 v[208:211], v155 offset:6144
	ds_read_b128 v[212:215], v155 offset:7168
	global_load_lds_dwordx4 v[148:149], off
	v_lshl_add_u64 v[148:149], s[26:27], 0, v[138:139]
	s_add_i32 m0, s39, 0xe000
	s_nop 0
	global_load_lds_dwordx4 v[148:149], off
	s_waitcnt vmcnt(8)
	s_waitcnt lgkmcnt(0)
	s_barrier
	s_setprio 1
	s_waitcnt lgkmcnt(0)
	v_mfma_f32_16x16x32_bf16 v[124:127], v[144:147], v[184:187], v[124:127]
	v_mfma_f32_16x16x32_bf16 v[120:123], v[160:163], v[184:187], v[120:123]
	v_mfma_f32_16x16x32_bf16 v[108:111], v[144:147], v[192:195], v[108:111]
	v_mfma_f32_16x16x32_bf16 v[104:107], v[160:163], v[192:195], v[104:107]
	v_mfma_f32_16x16x32_bf16 v[92:95], v[144:147], v[200:203], v[92:95]
	v_mfma_f32_16x16x32_bf16 v[88:91], v[160:163], v[200:203], v[88:91]
	v_mfma_f32_16x16x32_bf16 v[76:79], v[144:147], v[208:211], v[76:79]
	v_mfma_f32_16x16x32_bf16 v[72:75], v[160:163], v[208:211], v[72:75]
	v_mfma_f32_16x16x32_bf16 v[124:127], v[156:159], v[188:191], v[124:127]
	v_mfma_f32_16x16x32_bf16 v[120:123], v[164:167], v[188:191], v[120:123]
	v_mfma_f32_16x16x32_bf16 v[108:111], v[156:159], v[196:199], v[108:111]
	v_mfma_f32_16x16x32_bf16 v[104:107], v[164:167], v[196:199], v[104:107]
	v_mfma_f32_16x16x32_bf16 v[92:95], v[156:159], v[204:207], v[92:95]
	v_mfma_f32_16x16x32_bf16 v[88:91], v[164:167], v[204:207], v[88:91]
	v_mfma_f32_16x16x32_bf16 v[76:79], v[156:159], v[212:215], v[76:79]
	v_mfma_f32_16x16x32_bf16 v[72:75], v[164:167], v[212:215], v[72:75]
	s_setprio 0
	s_setprio 1
	v_mfma_f32_16x16x32_bf16 v[116:119], v[168:171], v[184:187], v[116:119]
	v_mfma_f32_16x16x32_bf16 v[112:115], v[176:179], v[184:187], v[112:115]
	v_mfma_f32_16x16x32_bf16 v[100:103], v[168:171], v[192:195], v[100:103]
	v_mfma_f32_16x16x32_bf16 v[96:99], v[176:179], v[192:195], v[96:99]
	v_mfma_f32_16x16x32_bf16 v[84:87], v[168:171], v[200:203], v[84:87]
	v_mfma_f32_16x16x32_bf16 v[80:83], v[176:179], v[200:203], v[80:83]
	v_mfma_f32_16x16x32_bf16 v[68:71], v[168:171], v[208:211], v[68:71]
	v_mfma_f32_16x16x32_bf16 v[64:67], v[176:179], v[208:211], v[64:67]
	v_mfma_f32_16x16x32_bf16 v[116:119], v[172:175], v[188:191], v[116:119]
	v_mfma_f32_16x16x32_bf16 v[112:115], v[180:183], v[188:191], v[112:115]
	v_mfma_f32_16x16x32_bf16 v[100:103], v[172:175], v[196:199], v[100:103]
	v_mfma_f32_16x16x32_bf16 v[96:99], v[180:183], v[196:199], v[96:99]
	v_mfma_f32_16x16x32_bf16 v[84:87], v[172:175], v[204:207], v[84:87]
	v_mfma_f32_16x16x32_bf16 v[80:83], v[180:183], v[204:207], v[80:83]
	v_mfma_f32_16x16x32_bf16 v[68:71], v[172:175], v[212:215], v[68:71]
	v_mfma_f32_16x16x32_bf16 v[64:67], v[180:183], v[212:215], v[64:67]
	s_setprio 0
	s_barrier
	s_add_i32 s26, s47, s38
	v_lshl_add_u64 v[148:149], s[30:31], 0, v[130:131]
	s_mov_b32 m0, s26
	ds_read_b128 v[184:187], v155 offset:16384
	ds_read_b128 v[188:191], v155 offset:17408
	ds_read_b128 v[192:195], v155 offset:18432
	ds_read_b128 v[196:199], v155 offset:19456
	ds_read_b128 v[200:203], v155 offset:20480
	ds_read_b128 v[204:207], v155 offset:21504
	ds_read_b128 v[208:211], v155 offset:22528
	ds_read_b128 v[212:215], v155 offset:23552
	global_load_lds_dwordx4 v[148:149], off
	s_add_i32 m0, s26, 0x2000
	s_add_u32 s26, s30, 0x300000
	v_lshl_add_u64 v[216:217], s[30:31], 0, v[134:135]
	s_addc_u32 s27, s31, 0
	s_add_i32 s54, s48, s38
	global_load_lds_dwordx4 v[216:217], off
	v_lshl_add_u64 v[218:219], s[26:27], 0, v[130:131]
	s_mov_b32 m0, s54
	v_lshl_add_u64 v[220:221], s[36:37], 0, v[132:133]
	global_load_lds_dwordx4 v[218:219], off
	v_lshl_add_u64 v[218:219], s[26:27], 0, v[134:135]
	s_add_i32 m0, s54, 0x2000
	s_nop 0
	global_load_lds_dwordx4 v[218:219], off
	v_lshl_add_u64 v[218:219], s[36:37], 0, v[128:129]
	s_waitcnt vmcnt(6)
	s_waitcnt lgkmcnt(0)
	s_barrier
	s_setprio 1
	s_waitcnt lgkmcnt(0)
	v_mfma_f32_16x16x32_bf16 v[60:63], v[144:147], v[184:187], v[60:63]
	v_mfma_f32_16x16x32_bf16 v[56:59], v[160:163], v[184:187], v[56:59]
	v_mfma_f32_16x16x32_bf16 v[44:47], v[144:147], v[192:195], v[44:47]
	v_mfma_f32_16x16x32_bf16 v[40:43], v[160:163], v[192:195], v[40:43]
	v_mfma_f32_16x16x32_bf16 v[28:31], v[144:147], v[200:203], v[28:31]
	v_mfma_f32_16x16x32_bf16 v[24:27], v[160:163], v[200:203], v[24:27]
	v_mfma_f32_16x16x32_bf16 v[12:15], v[144:147], v[208:211], v[12:15]
	v_mfma_f32_16x16x32_bf16 v[8:11], v[160:163], v[208:211], v[8:11]
	v_mfma_f32_16x16x32_bf16 v[60:63], v[156:159], v[188:191], v[60:63]
	v_mfma_f32_16x16x32_bf16 v[56:59], v[164:167], v[188:191], v[56:59]
	v_mfma_f32_16x16x32_bf16 v[44:47], v[156:159], v[196:199], v[44:47]
	v_mfma_f32_16x16x32_bf16 v[40:43], v[164:167], v[196:199], v[40:43]
	v_mfma_f32_16x16x32_bf16 v[28:31], v[156:159], v[204:207], v[28:31]
	v_mfma_f32_16x16x32_bf16 v[24:27], v[164:167], v[204:207], v[24:27]
	v_mfma_f32_16x16x32_bf16 v[12:15], v[156:159], v[212:215], v[12:15]
	v_mfma_f32_16x16x32_bf16 v[8:11], v[164:167], v[212:215], v[8:11]
	s_setprio 0
	s_setprio 1
	v_mfma_f32_16x16x32_bf16 v[52:55], v[168:171], v[184:187], v[52:55]
	v_mfma_f32_16x16x32_bf16 v[48:51], v[176:179], v[184:187], v[48:51]
	v_mfma_f32_16x16x32_bf16 v[36:39], v[168:171], v[192:195], v[36:39]
	v_mfma_f32_16x16x32_bf16 v[32:35], v[176:179], v[192:195], v[32:35]
	v_mfma_f32_16x16x32_bf16 v[20:23], v[168:171], v[200:203], v[20:23]
	v_mfma_f32_16x16x32_bf16 v[16:19], v[176:179], v[200:203], v[16:19]
	v_mfma_f32_16x16x32_bf16 v[4:7], v[168:171], v[208:211], v[4:7]
	v_mfma_f32_16x16x32_bf16 v[0:3], v[176:179], v[208:211], v[0:3]
	v_mfma_f32_16x16x32_bf16 v[52:55], v[172:175], v[188:191], v[52:55]
	v_mfma_f32_16x16x32_bf16 v[48:51], v[180:183], v[188:191], v[48:51]
	v_mfma_f32_16x16x32_bf16 v[36:39], v[172:175], v[196:199], v[36:39]
	v_mfma_f32_16x16x32_bf16 v[32:35], v[180:183], v[196:199], v[32:35]
	v_mfma_f32_16x16x32_bf16 v[20:23], v[172:175], v[204:207], v[20:23]
	v_mfma_f32_16x16x32_bf16 v[16:19], v[180:183], v[204:207], v[16:19]
	v_mfma_f32_16x16x32_bf16 v[4:7], v[172:175], v[212:215], v[4:7]
	v_mfma_f32_16x16x32_bf16 v[0:3], v[180:183], v[212:215], v[0:3]
	s_setprio 0
	s_barrier
	s_add_i32 s54, 0, 0x18000
	s_add_i32 s55, 0, 0x1c000
	v_add_u32_e32 v164, s54, v151
	v_add_u32_e32 v180, s55, v151
	ds_read_b128 v[144:147], v164
	ds_read_b128 v[156:159], v164 offset:1024
	ds_read_b128 v[160:163], v164 offset:2048
	ds_read_b128 v[164:167], v164 offset:3072
	ds_read_b128 v[168:171], v180
	ds_read_b128 v[172:175], v180 offset:1024
	ds_read_b128 v[176:179], v180 offset:2048
	ds_read_b128 v[180:183], v180 offset:3072
	s_add_u32 s26, s36, 0x300000
	s_addc_u32 s27, s37, 0
	s_mov_b32 m0, s41
	v_lshl_add_u64 v[222:223], s[26:27], 0, v[128:129]
	ds_read_b128 v[184:187], v155 offset:32768
	ds_read_b128 v[188:191], v155 offset:33792
	ds_read_b128 v[192:195], v155 offset:34816
	ds_read_b128 v[196:199], v155 offset:35840
	ds_read_b128 v[200:203], v155 offset:36864
	ds_read_b128 v[204:207], v155 offset:37888
	ds_read_b128 v[208:211], v155 offset:38912
	ds_read_b128 v[212:215], v155 offset:39936
	s_mov_b32 m0, s39
	s_nop 0
	global_load_lds_dwordx4 v[218:219], off
	s_mov_b32 m0, s40
	s_nop 0
	global_load_lds_dwordx4 v[220:221], off
	s_mov_b32 m0, s41
	s_nop 0
	global_load_lds_dwordx4 v[222:223], off
	v_lshl_add_u64 v[222:223], s[26:27], 0, v[132:133]
	s_mov_b32 m0, s42
	s_nop 0
	global_load_lds_dwordx4 v[222:223], off
	s_waitcnt vmcnt(8)
	s_waitcnt lgkmcnt(0)
	s_barrier
	s_setprio 1
	s_waitcnt lgkmcnt(0)
	v_mfma_f32_16x16x32_bf16 v[124:127], v[144:147], v[184:187], v[124:127]
	v_mfma_f32_16x16x32_bf16 v[120:123], v[160:163], v[184:187], v[120:123]
	v_mfma_f32_16x16x32_bf16 v[108:111], v[144:147], v[192:195], v[108:111]
	v_mfma_f32_16x16x32_bf16 v[104:107], v[160:163], v[192:195], v[104:107]
	v_mfma_f32_16x16x32_bf16 v[92:95], v[144:147], v[200:203], v[92:95]
	v_mfma_f32_16x16x32_bf16 v[88:91], v[160:163], v[200:203], v[88:91]
	v_mfma_f32_16x16x32_bf16 v[76:79], v[144:147], v[208:211], v[76:79]
	v_mfma_f32_16x16x32_bf16 v[72:75], v[160:163], v[208:211], v[72:75]
	v_mfma_f32_16x16x32_bf16 v[124:127], v[156:159], v[188:191], v[124:127]
	v_mfma_f32_16x16x32_bf16 v[120:123], v[164:167], v[188:191], v[120:123]
	v_mfma_f32_16x16x32_bf16 v[108:111], v[156:159], v[196:199], v[108:111]
	v_mfma_f32_16x16x32_bf16 v[104:107], v[164:167], v[196:199], v[104:107]
	v_mfma_f32_16x16x32_bf16 v[92:95], v[156:159], v[204:207], v[92:95]
	v_mfma_f32_16x16x32_bf16 v[88:91], v[164:167], v[204:207], v[88:91]
	v_mfma_f32_16x16x32_bf16 v[76:79], v[156:159], v[212:215], v[76:79]
	v_mfma_f32_16x16x32_bf16 v[72:75], v[164:167], v[212:215], v[72:75]
	s_setprio 0
	s_setprio 1
	v_mfma_f32_16x16x32_bf16 v[116:119], v[168:171], v[184:187], v[116:119]
	v_mfma_f32_16x16x32_bf16 v[112:115], v[176:179], v[184:187], v[112:115]
	v_mfma_f32_16x16x32_bf16 v[100:103], v[168:171], v[192:195], v[100:103]
	v_mfma_f32_16x16x32_bf16 v[96:99], v[176:179], v[192:195], v[96:99]
	v_mfma_f32_16x16x32_bf16 v[84:87], v[168:171], v[200:203], v[84:87]
	v_mfma_f32_16x16x32_bf16 v[80:83], v[176:179], v[200:203], v[80:83]
	v_mfma_f32_16x16x32_bf16 v[68:71], v[168:171], v[208:211], v[68:71]
	v_mfma_f32_16x16x32_bf16 v[64:67], v[176:179], v[208:211], v[64:67]
	v_mfma_f32_16x16x32_bf16 v[116:119], v[172:175], v[188:191], v[116:119]
	v_mfma_f32_16x16x32_bf16 v[112:115], v[180:183], v[188:191], v[112:115]
	v_mfma_f32_16x16x32_bf16 v[100:103], v[172:175], v[196:199], v[100:103]
	v_mfma_f32_16x16x32_bf16 v[96:99], v[180:183], v[196:199], v[96:99]
	v_mfma_f32_16x16x32_bf16 v[84:87], v[172:175], v[204:207], v[84:87]
	v_mfma_f32_16x16x32_bf16 v[80:83], v[180:183], v[204:207], v[80:83]
	v_mfma_f32_16x16x32_bf16 v[68:71], v[172:175], v[212:215], v[68:71]
	v_mfma_f32_16x16x32_bf16 v[64:67], v[180:183], v[212:215], v[64:67]
	s_setprio 0
	s_barrier
	s_add_i32 s26, s54, s38
	v_lshl_add_u64 v[148:149], v[148:149], 0, s[10:11]
	s_mov_b32 m0, s26
	ds_read_b128 v[184:187], v155 offset:49152
	ds_read_b128 v[188:191], v155 offset:50176
	ds_read_b128 v[192:195], v155 offset:51200
	ds_read_b128 v[196:199], v155 offset:52224
	ds_read_b128 v[200:203], v155 offset:53248
	ds_read_b128 v[204:207], v155 offset:54272
	ds_read_b128 v[208:211], v155 offset:55296
	ds_read_b128 v[212:215], v155 offset:56320
	global_load_lds_dwordx4 v[148:149], off
	s_add_i32 m0, s26, 0x2000
	s_add_u32 s26, s30, 0x300080
	v_lshl_add_u64 v[148:149], v[216:217], 0, s[10:11]
	s_addc_u32 s27, s31, 0
	s_add_i32 s30, s55, s38
	global_load_lds_dwordx4 v[148:149], off
	v_lshl_add_u64 v[148:149], s[26:27], 0, v[130:131]
	s_mov_b32 m0, s30
	s_nop 0
	global_load_lds_dwordx4 v[148:149], off
	v_lshl_add_u64 v[148:149], s[26:27], 0, v[134:135]
	s_add_i32 m0, s30, 0x2000
	s_nop 0
	global_load_lds_dwordx4 v[148:149], off
	v_lshl_add_u64 v[148:149], v[218:219], 0, s[10:11]
	s_mov_b32 m0, s44
	s_nop 0
	global_load_lds_dwordx4 v[148:149], off
	v_lshl_add_u64 v[148:149], v[220:221], 0, s[10:11]
	s_mov_b32 m0, s45
	s_nop 0
	global_load_lds_dwordx4 v[148:149], off
	s_waitcnt vmcnt(8)
	s_waitcnt lgkmcnt(0)
	s_barrier
	s_setprio 1
	s_waitcnt lgkmcnt(0)
	v_mfma_f32_16x16x32_bf16 v[60:63], v[144:147], v[184:187], v[60:63]
	v_mfma_f32_16x16x32_bf16 v[56:59], v[160:163], v[184:187], v[56:59]
	v_mfma_f32_16x16x32_bf16 v[44:47], v[144:147], v[192:195], v[44:47]
	v_mfma_f32_16x16x32_bf16 v[40:43], v[160:163], v[192:195], v[40:43]
	v_mfma_f32_16x16x32_bf16 v[28:31], v[144:147], v[200:203], v[28:31]
	v_mfma_f32_16x16x32_bf16 v[24:27], v[160:163], v[200:203], v[24:27]
	v_mfma_f32_16x16x32_bf16 v[12:15], v[144:147], v[208:211], v[12:15]
	v_mfma_f32_16x16x32_bf16 v[8:11], v[160:163], v[208:211], v[8:11]
	v_mfma_f32_16x16x32_bf16 v[60:63], v[156:159], v[188:191], v[60:63]
	v_mfma_f32_16x16x32_bf16 v[56:59], v[164:167], v[188:191], v[56:59]
	v_mfma_f32_16x16x32_bf16 v[44:47], v[156:159], v[196:199], v[44:47]
	v_mfma_f32_16x16x32_bf16 v[40:43], v[164:167], v[196:199], v[40:43]
	v_mfma_f32_16x16x32_bf16 v[28:31], v[156:159], v[204:207], v[28:31]
	v_mfma_f32_16x16x32_bf16 v[24:27], v[164:167], v[204:207], v[24:27]
	v_mfma_f32_16x16x32_bf16 v[12:15], v[156:159], v[212:215], v[12:15]
	v_mfma_f32_16x16x32_bf16 v[8:11], v[164:167], v[212:215], v[8:11]
	s_setprio 0
	s_setprio 1
	v_mfma_f32_16x16x32_bf16 v[52:55], v[168:171], v[184:187], v[52:55]
	v_mfma_f32_16x16x32_bf16 v[48:51], v[176:179], v[184:187], v[48:51]
	v_mfma_f32_16x16x32_bf16 v[36:39], v[168:171], v[192:195], v[36:39]
	v_mfma_f32_16x16x32_bf16 v[32:35], v[176:179], v[192:195], v[32:35]
	v_mfma_f32_16x16x32_bf16 v[20:23], v[168:171], v[200:203], v[20:23]
	v_mfma_f32_16x16x32_bf16 v[16:19], v[176:179], v[200:203], v[16:19]
	v_mfma_f32_16x16x32_bf16 v[4:7], v[168:171], v[208:211], v[4:7]
	v_mfma_f32_16x16x32_bf16 v[0:3], v[176:179], v[208:211], v[0:3]
	v_mfma_f32_16x16x32_bf16 v[52:55], v[172:175], v[188:191], v[52:55]
	v_mfma_f32_16x16x32_bf16 v[48:51], v[180:183], v[188:191], v[48:51]
	v_mfma_f32_16x16x32_bf16 v[36:39], v[172:175], v[196:199], v[36:39]
	v_mfma_f32_16x16x32_bf16 v[32:35], v[180:183], v[196:199], v[32:35]
	v_mfma_f32_16x16x32_bf16 v[20:23], v[172:175], v[204:207], v[20:23]
	v_mfma_f32_16x16x32_bf16 v[16:19], v[180:183], v[204:207], v[16:19]
	v_mfma_f32_16x16x32_bf16 v[4:7], v[172:175], v[212:215], v[4:7]
	v_mfma_f32_16x16x32_bf16 v[0:3], v[180:183], v[212:215], v[0:3]
	s_setprio 0
	s_barrier
	s_add_i32 s53, s53, 2
	s_add_u32 s34, s34, 0x100
	s_addc_u32 s35, s35, 0
	s_cmpk_gt_u32 s53, 0xbd
	s_mov_b64 s[26:27], s[28:29]
	s_cbranch_scc0 .LBB0_1077
	s_and_b64 vcc, exec, s[12:13]
	s_cbranch_vccz .LBB0_1080
	s_barrier

.LBB0_1313:
	ds_read_b128 v[48:51], v163
	ds_read_b128 v[52:55], v163 offset:1024
	ds_read_b128 v[152:155], v163 offset:2048
	ds_read_b128 v[156:159], v163 offset:3072
	ds_read_b128 v[168:171], v164
	ds_read_b128 v[172:175], v164 offset:1024
	ds_read_b128 v[176:179], v164 offset:2048
	ds_read_b128 v[180:183], v164 offset:3072
	s_add_u32 s42, s40, 0xfff00080
	s_addc_u32 s43, s41, -1
	s_cmp_eq_u32 s60, 60
	s_cselect_b32 s45, s14, s43
	s_cselect_b32 s44, s29, s42
	s_cselect_b32 s43, s27, s35
	s_cselect_b32 s42, s39, s34
	v_lshl_add_u64 v[216:217], s[40:41], 0, v[144:145]
	s_add_i32 m0, s47, 0xc000
	ds_read_b128 v[184:187], v165
	ds_read_b128 v[188:191], v165 offset:1024
	ds_read_b128 v[192:195], v165 offset:2048
	ds_read_b128 v[196:199], v165 offset:3072
	ds_read_b128 v[200:203], v165 offset:4096
	ds_read_b128 v[204:207], v165 offset:5120
	ds_read_b128 v[208:211], v165 offset:6144
	ds_read_b128 v[212:215], v165 offset:7168
	global_load_lds_dwordx4 v[216:217], off
	v_lshl_add_u64 v[216:217], s[40:41], 0, v[146:147]
	s_add_i32 m0, s47, 0xe000
	s_nop 0
	global_load_lds_dwordx4 v[216:217], off
	s_waitcnt vmcnt(8)
	s_waitcnt lgkmcnt(0)
	s_barrier
	s_setprio 1
	s_waitcnt lgkmcnt(0)
	v_mfma_f32_16x16x32_bf16 v[44:47], v[48:51], v[184:187], v[44:47]
	v_mfma_f32_16x16x32_bf16 v[40:43], v[152:155], v[184:187], v[40:43]
	v_mfma_f32_16x16x32_bf16 v[124:127], v[48:51], v[192:195], v[124:127]
	v_mfma_f32_16x16x32_bf16 v[120:123], v[152:155], v[192:195], v[120:123]
	v_mfma_f32_16x16x32_bf16 v[108:111], v[48:51], v[200:203], v[108:111]
	v_mfma_f32_16x16x32_bf16 v[104:107], v[152:155], v[200:203], v[104:107]
	v_mfma_f32_16x16x32_bf16 v[92:95], v[48:51], v[208:211], v[92:95]
	v_mfma_f32_16x16x32_bf16 v[88:91], v[152:155], v[208:211], v[88:91]
	v_mfma_f32_16x16x32_bf16 v[44:47], v[52:55], v[188:191], v[44:47]
	v_mfma_f32_16x16x32_bf16 v[40:43], v[156:159], v[188:191], v[40:43]
	v_mfma_f32_16x16x32_bf16 v[124:127], v[52:55], v[196:199], v[124:127]
	v_mfma_f32_16x16x32_bf16 v[120:123], v[156:159], v[196:199], v[120:123]
	v_mfma_f32_16x16x32_bf16 v[108:111], v[52:55], v[204:207], v[108:111]
	v_mfma_f32_16x16x32_bf16 v[104:107], v[156:159], v[204:207], v[104:107]
	v_mfma_f32_16x16x32_bf16 v[92:95], v[52:55], v[212:215], v[92:95]
	v_mfma_f32_16x16x32_bf16 v[88:91], v[156:159], v[212:215], v[88:91]
	s_setprio 0
	s_setprio 1
	v_mfma_f32_16x16x32_bf16 v[132:135], v[168:171], v[184:187], v[132:135]
	v_mfma_f32_16x16x32_bf16 v[128:131], v[176:179], v[184:187], v[128:131]
	v_mfma_f32_16x16x32_bf16 v[116:119], v[168:171], v[192:195], v[116:119]
	v_mfma_f32_16x16x32_bf16 v[112:115], v[176:179], v[192:195], v[112:115]
	v_mfma_f32_16x16x32_bf16 v[100:103], v[168:171], v[200:203], v[100:103]
	v_mfma_f32_16x16x32_bf16 v[96:99], v[176:179], v[200:203], v[96:99]
	v_mfma_f32_16x16x32_bf16 v[84:87], v[168:171], v[208:211], v[84:87]
	v_mfma_f32_16x16x32_bf16 v[80:83], v[176:179], v[208:211], v[80:83]
	v_mfma_f32_16x16x32_bf16 v[132:135], v[172:175], v[188:191], v[132:135]
	v_mfma_f32_16x16x32_bf16 v[128:131], v[180:183], v[188:191], v[128:131]
	v_mfma_f32_16x16x32_bf16 v[116:119], v[172:175], v[196:199], v[116:119]
	v_mfma_f32_16x16x32_bf16 v[112:115], v[180:183], v[196:199], v[112:115]
	v_mfma_f32_16x16x32_bf16 v[100:103], v[172:175], v[204:207], v[100:103]
	v_mfma_f32_16x16x32_bf16 v[96:99], v[180:183], v[204:207], v[96:99]
	v_mfma_f32_16x16x32_bf16 v[84:87], v[172:175], v[212:215], v[84:87]
	v_mfma_f32_16x16x32_bf16 v[80:83], v[180:183], v[212:215], v[80:83]
	s_setprio 0
	s_barrier
	s_add_i32 s61, s56, s46
	v_lshl_add_u64 v[216:217], s[42:43], 0, v[138:139]
	s_mov_b32 m0, s61
	ds_read_b128 v[184:187], v165 offset:16384
	ds_read_b128 v[188:191], v165 offset:17408
	ds_read_b128 v[192:195], v165 offset:18432
	ds_read_b128 v[196:199], v165 offset:19456
	ds_read_b128 v[200:203], v165 offset:20480
	ds_read_b128 v[204:207], v165 offset:21504
	ds_read_b128 v[208:211], v165 offset:22528
	ds_read_b128 v[212:215], v165 offset:23552
	global_load_lds_dwordx4 v[216:217], off
	s_add_i32 m0, s61, 0x2000
	s_add_u32 s62, s42, 0x100000
	v_lshl_add_u64 v[218:219], s[42:43], 0, v[142:143]
	s_addc_u32 s63, s43, 0
	s_add_i32 s61, s57, s46
	global_load_lds_dwordx4 v[218:219], off
	v_lshl_add_u64 v[220:221], s[62:63], 0, v[138:139]
	s_mov_b32 m0, s61
	v_lshl_add_u64 v[222:223], s[44:45], 0, v[140:141]
	global_load_lds_dwordx4 v[220:221], off
	v_lshl_add_u64 v[220:221], s[62:63], 0, v[142:143]
	s_add_i32 m0, s61, 0x2000
	s_nop 0
	global_load_lds_dwordx4 v[220:221], off
	v_lshl_add_u64 v[220:221], s[44:45], 0, v[136:137]
	s_waitcnt vmcnt(6)
	s_waitcnt lgkmcnt(0)
	s_barrier
	s_setprio 1
	s_waitcnt lgkmcnt(0)
	v_mfma_f32_16x16x32_bf16 v[76:79], v[48:51], v[184:187], v[76:79]
	v_mfma_f32_16x16x32_bf16 v[72:75], v[152:155], v[184:187], v[72:75]
	v_mfma_f32_16x16x32_bf16 v[60:63], v[48:51], v[192:195], v[60:63]
	v_mfma_f32_16x16x32_bf16 v[56:59], v[152:155], v[192:195], v[56:59]
	v_mfma_f32_16x16x32_bf16 v[28:31], v[48:51], v[200:203], v[28:31]
	v_mfma_f32_16x16x32_bf16 v[24:27], v[152:155], v[200:203], v[24:27]
	v_mfma_f32_16x16x32_bf16 v[12:15], v[48:51], v[208:211], v[12:15]
	v_mfma_f32_16x16x32_bf16 v[8:11], v[152:155], v[208:211], v[8:11]
	v_mfma_f32_16x16x32_bf16 v[76:79], v[52:55], v[188:191], v[76:79]
	v_mfma_f32_16x16x32_bf16 v[72:75], v[156:159], v[188:191], v[72:75]
	v_mfma_f32_16x16x32_bf16 v[60:63], v[52:55], v[196:199], v[60:63]
	v_mfma_f32_16x16x32_bf16 v[56:59], v[156:159], v[196:199], v[56:59]
	v_mfma_f32_16x16x32_bf16 v[28:31], v[52:55], v[204:207], v[28:31]
	v_mfma_f32_16x16x32_bf16 v[24:27], v[156:159], v[204:207], v[24:27]
	v_mfma_f32_16x16x32_bf16 v[12:15], v[52:55], v[212:215], v[12:15]
	v_mfma_f32_16x16x32_bf16 v[8:11], v[156:159], v[212:215], v[8:11]
	s_setprio 0
	s_setprio 1
	v_mfma_f32_16x16x32_bf16 v[36:39], v[168:171], v[192:195], v[36:39]
	v_mfma_f32_16x16x32_bf16 v[32:35], v[176:179], v[192:195], v[32:35]
	v_mfma_f32_16x16x32_bf16 v[20:23], v[168:171], v[200:203], v[20:23]
	v_mfma_f32_16x16x32_bf16 v[16:19], v[176:179], v[200:203], v[16:19]
	v_mfma_f32_16x16x32_bf16 v[4:7], v[168:171], v[208:211], v[4:7]
	v_mfma_f32_16x16x32_bf16 v[0:3], v[176:179], v[208:211], v[0:3]
	v_mfma_f32_16x16x32_bf16 v[48:51], v[168:171], v[184:187], v[68:71]
	v_mfma_f32_16x16x32_bf16 v[52:55], v[176:179], v[184:187], v[64:67]
	v_mfma_f32_16x16x32_bf16 v[36:39], v[172:175], v[196:199], v[36:39]
	v_mfma_f32_16x16x32_bf16 v[32:35], v[180:183], v[196:199], v[32:35]
	v_mfma_f32_16x16x32_bf16 v[20:23], v[172:175], v[204:207], v[20:23]
	v_mfma_f32_16x16x32_bf16 v[16:19], v[180:183], v[204:207], v[16:19]
	v_mfma_f32_16x16x32_bf16 v[4:7], v[172:175], v[212:215], v[4:7]
	v_mfma_f32_16x16x32_bf16 v[0:3], v[180:183], v[212:215], v[0:3]
	v_mfma_f32_16x16x32_bf16 v[48:51], v[172:175], v[188:191], v[48:51]
	v_mfma_f32_16x16x32_bf16 v[52:55], v[180:183], v[188:191], v[52:55]
	s_setprio 0
	s_barrier
	s_add_i32 s61, 0, 0x18000
	s_add_i32 s62, 0, 0x1c000
	v_add_u32_e32 v156, s61, v161
	v_add_u32_e32 v167, s62, v161
	ds_read_b128 v[64:67], v156
	ds_read_b128 v[68:71], v156 offset:1024
	ds_read_b128 v[152:155], v156 offset:2048
	ds_read_b128 v[156:159], v156 offset:3072
	ds_read_b128 v[168:171], v167
	ds_read_b128 v[172:175], v167 offset:1024
	ds_read_b128 v[176:179], v167 offset:2048
	ds_read_b128 v[180:183], v167 offset:3072
	s_add_u32 s44, s44, 0x100000
	s_addc_u32 s45, s45, 0
	s_mov_b32 m0, s49
	v_lshl_add_u64 v[226:227], s[44:45], 0, v[136:137]
	ds_read_b128 v[184:187], v165 offset:32768
	ds_read_b128 v[188:191], v165 offset:33792
	ds_read_b128 v[192:195], v165 offset:34816
	ds_read_b128 v[196:199], v165 offset:35840
	ds_read_b128 v[200:203], v165 offset:36864
	ds_read_b128 v[204:207], v165 offset:37888
	ds_read_b128 v[208:211], v165 offset:38912
	ds_read_b128 v[212:215], v165 offset:39936
	s_mov_b32 m0, s47
	s_nop 0
	global_load_lds_dwordx4 v[220:221], off
	s_mov_b32 m0, s48
	s_nop 0
	global_load_lds_dwordx4 v[222:223], off
	s_mov_b32 m0, s49
	s_nop 0
	global_load_lds_dwordx4 v[226:227], off
	v_lshl_add_u64 v[226:227], s[44:45], 0, v[140:141]
	s_mov_b32 m0, s50
	s_nop 0
	global_load_lds_dwordx4 v[226:227], off
	s_waitcnt vmcnt(8)
	s_waitcnt lgkmcnt(0)
	s_barrier
	s_setprio 1
	s_waitcnt lgkmcnt(0)
	v_mfma_f32_16x16x32_bf16 v[44:47], v[64:67], v[184:187], v[44:47]
	v_mfma_f32_16x16x32_bf16 v[40:43], v[152:155], v[184:187], v[40:43]
	v_mfma_f32_16x16x32_bf16 v[124:127], v[64:67], v[192:195], v[124:127]
	v_mfma_f32_16x16x32_bf16 v[120:123], v[152:155], v[192:195], v[120:123]
	v_mfma_f32_16x16x32_bf16 v[108:111], v[64:67], v[200:203], v[108:111]
	v_mfma_f32_16x16x32_bf16 v[104:107], v[152:155], v[200:203], v[104:107]
	v_mfma_f32_16x16x32_bf16 v[92:95], v[64:67], v[208:211], v[92:95]
	v_mfma_f32_16x16x32_bf16 v[88:91], v[152:155], v[208:211], v[88:91]
	v_mfma_f32_16x16x32_bf16 v[44:47], v[68:71], v[188:191], v[44:47]
	v_mfma_f32_16x16x32_bf16 v[40:43], v[156:159], v[188:191], v[40:43]
	v_mfma_f32_16x16x32_bf16 v[124:127], v[68:71], v[196:199], v[124:127]
	v_mfma_f32_16x16x32_bf16 v[120:123], v[156:159], v[196:199], v[120:123]
	v_mfma_f32_16x16x32_bf16 v[108:111], v[68:71], v[204:207], v[108:111]
	v_mfma_f32_16x16x32_bf16 v[104:107], v[156:159], v[204:207], v[104:107]
	v_mfma_f32_16x16x32_bf16 v[92:95], v[68:71], v[212:215], v[92:95]
	v_mfma_f32_16x16x32_bf16 v[88:91], v[156:159], v[212:215], v[88:91]
	s_setprio 0
	s_setprio 1
	v_mfma_f32_16x16x32_bf16 v[132:135], v[168:171], v[184:187], v[132:135]
	v_mfma_f32_16x16x32_bf16 v[128:131], v[176:179], v[184:187], v[128:131]
	v_mfma_f32_16x16x32_bf16 v[116:119], v[168:171], v[192:195], v[116:119]
	v_mfma_f32_16x16x32_bf16 v[112:115], v[176:179], v[192:195], v[112:115]
	v_mfma_f32_16x16x32_bf16 v[100:103], v[168:171], v[200:203], v[100:103]
	v_mfma_f32_16x16x32_bf16 v[96:99], v[176:179], v[200:203], v[96:99]
	v_mfma_f32_16x16x32_bf16 v[84:87], v[168:171], v[208:211], v[84:87]
	v_mfma_f32_16x16x32_bf16 v[80:83], v[176:179], v[208:211], v[80:83]
	v_mfma_f32_16x16x32_bf16 v[132:135], v[172:175], v[188:191], v[132:135]
	v_mfma_f32_16x16x32_bf16 v[128:131], v[180:183], v[188:191], v[128:131]
	v_mfma_f32_16x16x32_bf16 v[116:119], v[172:175], v[196:199], v[116:119]
	v_mfma_f32_16x16x32_bf16 v[112:115], v[180:183], v[196:199], v[112:115]
	v_mfma_f32_16x16x32_bf16 v[100:103], v[172:175], v[204:207], v[100:103]
	v_mfma_f32_16x16x32_bf16 v[96:99], v[180:183], v[204:207], v[96:99]
	v_mfma_f32_16x16x32_bf16 v[84:87], v[172:175], v[212:215], v[84:87]
	v_mfma_f32_16x16x32_bf16 v[80:83], v[180:183], v[212:215], v[80:83]
	s_setprio 0
	s_barrier
	s_add_i32 s44, s61, s46
	v_lshl_add_u64 v[216:217], v[216:217], 0, s[22:23]
	s_mov_b32 m0, s44
	ds_read_b128 v[184:187], v165 offset:49152
	ds_read_b128 v[188:191], v165 offset:50176
	ds_read_b128 v[192:195], v165 offset:51200
	ds_read_b128 v[196:199], v165 offset:52224
	ds_read_b128 v[200:203], v165 offset:53248
	ds_read_b128 v[204:207], v165 offset:54272
	ds_read_b128 v[208:211], v165 offset:55296
	ds_read_b128 v[212:215], v165 offset:56320
	global_load_lds_dwordx4 v[216:217], off
	s_add_i32 m0, s44, 0x2000
	s_add_u32 s42, s42, 0x100080
	v_lshl_add_u64 v[216:217], v[218:219], 0, s[22:23]
	s_addc_u32 s43, s43, 0
	s_add_i32 s44, s62, s46
	global_load_lds_dwordx4 v[216:217], off
	v_lshl_add_u64 v[216:217], s[42:43], 0, v[138:139]
	s_mov_b32 m0, s44
	s_nop 0
	global_load_lds_dwordx4 v[216:217], off
	v_lshl_add_u64 v[216:217], s[42:43], 0, v[142:143]
	s_add_i32 m0, s44, 0x2000
	s_nop 0
	global_load_lds_dwordx4 v[216:217], off
	v_lshl_add_u64 v[216:217], v[220:221], 0, s[22:23]
	s_mov_b32 m0, s52
	s_nop 0
	global_load_lds_dwordx4 v[216:217], off
	v_lshl_add_u64 v[216:217], v[222:223], 0, s[22:23]
	s_mov_b32 m0, s53
	s_nop 0
	global_load_lds_dwordx4 v[216:217], off
	s_waitcnt vmcnt(8)
	s_waitcnt lgkmcnt(0)
	s_barrier
	s_setprio 1
	s_waitcnt lgkmcnt(0)
	v_mfma_f32_16x16x32_bf16 v[76:79], v[64:67], v[184:187], v[76:79]
	v_mfma_f32_16x16x32_bf16 v[72:75], v[152:155], v[184:187], v[72:75]
	v_mfma_f32_16x16x32_bf16 v[60:63], v[64:67], v[192:195], v[60:63]
	v_mfma_f32_16x16x32_bf16 v[56:59], v[152:155], v[192:195], v[56:59]
	v_mfma_f32_16x16x32_bf16 v[28:31], v[64:67], v[200:203], v[28:31]
	v_mfma_f32_16x16x32_bf16 v[24:27], v[152:155], v[200:203], v[24:27]
	v_mfma_f32_16x16x32_bf16 v[12:15], v[64:67], v[208:211], v[12:15]
	v_mfma_f32_16x16x32_bf16 v[8:11], v[152:155], v[208:211], v[8:11]
	v_mfma_f32_16x16x32_bf16 v[76:79], v[68:71], v[188:191], v[76:79]
	v_mfma_f32_16x16x32_bf16 v[72:75], v[156:159], v[188:191], v[72:75]
	v_mfma_f32_16x16x32_bf16 v[60:63], v[68:71], v[196:199], v[60:63]
	v_mfma_f32_16x16x32_bf16 v[56:59], v[156:159], v[196:199], v[56:59]
	v_mfma_f32_16x16x32_bf16 v[28:31], v[68:71], v[204:207], v[28:31]
	v_mfma_f32_16x16x32_bf16 v[24:27], v[156:159], v[204:207], v[24:27]
	v_mfma_f32_16x16x32_bf16 v[12:15], v[68:71], v[212:215], v[12:15]
	v_mfma_f32_16x16x32_bf16 v[8:11], v[156:159], v[212:215], v[8:11]
	s_setprio 0
	s_setprio 1
	v_mfma_f32_16x16x32_bf16 v[48:51], v[168:171], v[184:187], v[48:51]
	v_mfma_f32_16x16x32_bf16 v[68:71], v[172:175], v[188:191], v[48:51]
	v_mfma_f32_16x16x32_bf16 v[48:51], v[176:179], v[184:187], v[52:55]
	v_mfma_f32_16x16x32_bf16 v[36:39], v[168:171], v[192:195], v[36:39]
	v_mfma_f32_16x16x32_bf16 v[32:35], v[176:179], v[192:195], v[32:35]
	v_mfma_f32_16x16x32_bf16 v[20:23], v[168:171], v[200:203], v[20:23]
	v_mfma_f32_16x16x32_bf16 v[16:19], v[176:179], v[200:203], v[16:19]
	v_mfma_f32_16x16x32_bf16 v[4:7], v[168:171], v[208:211], v[4:7]
	v_mfma_f32_16x16x32_bf16 v[0:3], v[176:179], v[208:211], v[0:3]
	v_mfma_f32_16x16x32_bf16 v[64:67], v[180:183], v[188:191], v[48:51]
	v_mfma_f32_16x16x32_bf16 v[36:39], v[172:175], v[196:199], v[36:39]
	v_mfma_f32_16x16x32_bf16 v[32:35], v[180:183], v[196:199], v[32:35]
	v_mfma_f32_16x16x32_bf16 v[20:23], v[172:175], v[204:207], v[20:23]
	v_mfma_f32_16x16x32_bf16 v[16:19], v[180:183], v[204:207], v[16:19]
	v_mfma_f32_16x16x32_bf16 v[4:7], v[172:175], v[212:215], v[4:7]
	v_mfma_f32_16x16x32_bf16 v[0:3], v[180:183], v[212:215], v[0:3]
	s_setprio 0
	s_barrier
	s_add_i32 s60, s60, 2
	s_add_u32 s40, s40, 0x100
	s_addc_u32 s41, s41, 0
	s_add_u32 s34, s34, 0x100
	s_addc_u32 s35, s35, 0
	s_cmp_gt_u32 s60, 61
	s_cbranch_scc0 .LBB0_1313
	s_and_b64 vcc, exec, s[24:25]
	s_cbranch_vccz .LBB0_1316
	s_barrier
